# ALiBi bias of copy-1 diff-attention tiles via f32 MFMA rank-2 update (v_mfma_f32_32x32x2_f32), QK chains write softmax registers directly; per-element f32 FMA only on diagonal tile
# speedup vs baseline: 1.0319x; 1.0020x over previous
; template <int DQK, int DV, bool BIAS> ...
;     ...
;     int tid_ = threadIdx.x; asm volatile("" : "+v"(tid_));
;     const int tid = tid_, lane = tid & 63, r32 = lane & 31, hi = lane >> 5;
;     const bool isY = false;
;     bf16x8 qf[NKS];
; #pragma unroll
;     for (int ks = 0; ks < NKS; ++ks) qf[ks] = ks < 4 ? *(const bf16x8*)(Qw + (size_t)r32 * ldq + ks * 16 + hi * 8) : *(const bf16x8*)(Q2w + (size_t)r32 * ldq2 + (ks - 4) * 16 + hi * 8);
; #pragma unroll
;     for (int ks = 0; ks < 4; ++ks) qf[ks] = scale_frag(qf[ks], cs);
;     if constexpr (DQK == 96) {
;         const float* rp = ropetab + ((size_t)(qpos0 + r32) * 16) * 2;
; #pragma unroll
;         for (int ks = 4; ks < 6; ++ks) {
;             const f32x4 c0 = *(const f32x4*)(rp + ((ks - 4) * 8 + hi * 4) * 2), c1 = *(const f32x4*)(rp + ((ks - 4) * 8 + hi * 4 + 2) * 2);
;             const u32x4 w = __builtin_bit_cast(u32x4, qf[ks]); u32x4 ow;
;             { const float a = bflo(w.x) * cs, b = bfhi(w.x) * cs; ow.x = cvtpk(a * c0[0] - b * c0[1], a * c0[1] + b * c0[0]); }
;             { const float a = bflo(w.y) * cs, b = bfhi(w.y) * cs; ow.y = cvtpk(a * c0[2] - b * c0[3], a * c0[3] + b * c0[2]); }
;             { const float a = bflo(w.z) * cs, b = bfhi(w.z) * cs; ow.z = cvtpk(a * c1[0] - b * c1[1], a * c1[1] + b * c1[0]); }
;             { const float a = bflo(w.w) * cs, b = bfhi(w.w) * cs; ow.w = cvtpk(a * c1[2] - b * c1[3], a * c1[3] + b * c1[2]); }
;             qf[ks] = __builtin_bit_cast(bf16x8, ow);
;         }
;     }
; #pragma unroll
;     for (int d = 0; d < NDT; ++d)
; #pragma unroll
;         for (int r = 0; r < 16; ++r) o[d][r] = 0.f;
; #pragma unroll
;     for (int ks = 0; ks < NKS; ++ks) asm volatile("" : "+v"(qf[ks]));
;     float mhat = 0.f, l = 0.f; f32x16 negm;
; #pragma unroll
;     for (int r = 0; r < 16; ++r) negm[r] = 0.f;
;     constexpr int TPB = (DV == 64) ? 2 : 1, NG = SEQL / 64 / TPB;
;     u32x4 kreg[TPB], k2reg[TPB], vreg[TPB][NVL];
;     const bf16_t* kptr = Kg + (size_t)(tid >> 3) * ldk + (tid & 7) * 8;
;     const bf16_t* k2ptr = (DQK == 96) ? K2g + (size_t)(tid >> 2) * ldk2 + (tid & 3) * 8 : nullptr;
;     ...
;     u32x4 pw[4];
; #pragma unroll
;     for (int j = 0; j < TPB; ++j) { ATT_LOAD(j, j); ATT_STORE(j, j); }
; #pragma unroll
;     for (int j = 0; j < TPB; ++j) ATT_LOAD(TPB + j, j);
;     const float qp = (float)(qpos0 + r32);
.LBB0_573:
	s_cmp_lt_i32 s24, 5
	s_cselect_b64 s[4:5], -1, 0
	s_cmp_gt_i32 s25, 4
	s_cselect_b64 s[6:7], -1, 0
	s_and_b64 s[4:5], s[4:5], s[6:7]
	s_andn2_b64 vcc, exec, s[4:5]
	s_cbranch_vccnz .LBB0_751
	s_mov_b64 s[20:21], s[0:1]
	v_mov_b32_e32 v169, v1
	s_load_dwordx2 s[16:17], s[20:21], 0x118
	s_ashr_i32 s4, s33, 6
	v_readfirstlane_b32 s3, v169
	s_ashr_i32 s50, s3, 6
	s_ashr_i32 s5, s4, 31
	s_lshl_b32 s3, s33, 8
	s_lshl_b64 s[6:7], s[4:5], 12
	s_and_b32 s27, s3, 0xf00
	s_lshl_b32 s46, s50, 5
	s_bfe_u32 s8, s33, 0x20004
	s_or_b32 s3, s6, s27
	s_ashr_i32 s47, s46, 31
	s_add_u32 s5, s3, s46
	s_addc_u32 s6, s7, s47
	s_not_b32 s3, s8
	s_mulk_i32 s6, 0x1940
	s_mul_hi_u32 s7, s5, 0x1940
	s_lshl_b32 s3, s3, 1
	s_add_i32 s7, s7, s6
	s_mulk_i32 s5, 0x1940
	s_waitcnt lgkmcnt(0)
	s_add_u32 s5, s16, s5
	v_mov_b32_e32 v32, v1
	s_addc_u32 s6, s17, s7
	s_lshl_b32 s9, s8, 8
	s_add_u32 s18, s5, s9
	v_and_b32_e32 v33, 31, v32
	v_mul_u32_u24_e32 v2, 0xca0, v33
	s_addc_u32 s19, s6, 0
	v_bfe_u32 v34, v32, 5, 1
	v_lshlrev_b32_e32 v150, 1, v2
	v_mov_b32_e32 v151, 0
	v_lshl_add_u64 v[2:3], s[18:19], 0, v[150:151]
	v_lshlrev_b32_e32 v150, 4, v34
	v_lshl_add_u64 v[18:19], v[2:3], 0, v[150:151]
	global_load_dwordx4 v[2:5], v[18:19], off
	global_load_dwordx4 v[6:9], v[18:19], off offset:32
	global_load_dwordx4 v[10:13], v[18:19], off offset:64
	global_load_dwordx4 v[14:17], v[18:19], off offset:96
	s_movk_i32 s7, 0x1940
	s_mov_b32 s6, 0x3e38aa3b
	s_mul_i32 s49, s4, 0x1940000
	s_mul_hi_i32 s48, s4, 0x1940000
	s_add_u32 s4, s16, s49
	s_addc_u32 s5, s17, s48
	s_add_u32 s4, s4, s9
	s_addc_u32 s5, s5, 0
	s_mov_b32 s8, 0x65000
	v_lshlrev_b32_e32 v173, 2, v34
	s_mov_b32 s22, 0xc1000000
	s_mov_b32 s34, 0xc1200000
	s_mov_b32 s36, 0xc1800000
	s_mov_b32 s38, 0xc1900000
	s_mov_b32 s40, 0xc1c00000
	s_mov_b32 s42, 0xc1d00000
	s_mov_b32 s51, 0
	s_mov_b32 s23, 0xc1100000
	s_mov_b32 s35, 0xc1300000
	s_mov_b32 s37, 0xc1880000
	s_mov_b32 s39, 0xc1980000
	s_mov_b32 s41, 0xc1c80000
	s_mov_b32 s43, 0xc1d80000
	s_mov_b32 s52, 0x41000000
	v_mov_b32_e32 v176, v151
	v_mov_b32_e32 v66, v151
	v_mov_b32_e32 v67, v151
	v_mov_b32_e32 v68, v151
	v_mov_b32_e32 v69, v151
	v_mov_b32_e32 v70, v151
	v_mov_b32_e32 v71, v151
	v_mov_b32_e32 v72, v151
	v_mov_b32_e32 v73, v151
	v_mov_b32_e32 v74, v151
	v_mov_b32_e32 v75, v151
	v_mov_b32_e32 v76, v151
	v_mov_b32_e32 v77, v151
	v_mov_b32_e32 v78, v151
	v_mov_b32_e32 v79, v151
	v_mov_b32_e32 v80, v151
	v_mov_b32_e32 v81, v151
	s_waitcnt vmcnt(0)
	v_lshlrev_b32_e32 v18, 16, v2
	v_and_b32_e32 v19, 0xffff0000, v2
	v_lshlrev_b32_e32 v2, 16, v3
	v_and_b32_e32 v3, 0xffff0000, v3
	v_lshlrev_b32_e32 v30, 16, v14
	v_pk_mul_f32 v[2:3], v[2:3], s[6:7] op_sel_hi:[1,0]
	v_and_b32_e32 v31, 0xffff0000, v14
	v_cvt_pk_bf16_f32 v115, v2, v3
	v_pk_mul_f32 v[2:3], v[30:31], s[6:7] op_sel_hi:[1,0]
	v_lshlrev_b32_e32 v22, 16, v6
	v_cvt_pk_bf16_f32 v126, v2, v3
	v_lshlrev_b32_e32 v2, 16, v15
	v_and_b32_e32 v3, 0xffff0000, v15
	v_pk_mul_f32 v[2:3], v[2:3], s[6:7] op_sel_hi:[1,0]
	v_and_b32_e32 v23, 0xffff0000, v6
	v_cvt_pk_bf16_f32 v127, v2, v3
	v_lshlrev_b32_e32 v2, 16, v16
	v_and_b32_e32 v3, 0xffff0000, v16
	v_pk_mul_f32 v[2:3], v[2:3], s[6:7] op_sel_hi:[1,0]
	v_lshlrev_b32_e32 v24, 16, v8
	v_cvt_pk_bf16_f32 v128, v2, v3
	v_lshlrev_b32_e32 v2, 16, v17
	v_and_b32_e32 v3, 0xffff0000, v17
	v_and_b32_e32 v25, 0xffff0000, v8
	v_pk_mul_f32 v[22:23], v[22:23], s[6:7] op_sel_hi:[1,0]
	v_pk_mul_f32 v[2:3], v[2:3], s[6:7] op_sel_hi:[1,0]
	v_lshlrev_b32_e32 v20, 16, v4
	v_and_b32_e32 v21, 0xffff0000, v4
	v_lshlrev_b32_e32 v4, 16, v5
	v_and_b32_e32 v5, 0xffff0000, v5
	v_pk_mul_f32 v[24:25], v[24:25], s[6:7] op_sel_hi:[1,0]
	v_cvt_pk_bf16_f32 v118, v22, v23
	v_cvt_pk_bf16_f32 v129, v2, v3
	v_ashrrev_i32_e32 v22, 3, v32
	v_mov_b64_e32 v[2:3], s[4:5]
	v_lshlrev_b32_e32 v23, 4, v32
	v_pk_mul_f32 v[4:5], v[4:5], s[6:7] op_sel_hi:[1,0]
	v_cvt_pk_bf16_f32 v120, v24, v25
	v_mad_i64_i32 v[2:3], s[10:11], v22, s7, v[2:3]
	v_and_b32_e32 v14, 0x70, v23
	v_mov_b32_e32 v15, v151
	v_bfe_u32 v24, v32, 2, 6
	v_cvt_pk_bf16_f32 v117, v4, v5
	v_lshl_add_u64 v[144:145], v[2:3], 0, v[14:15]
	v_mul_u32_u24_e32 v2, 0xca0, v24
	v_lshlrev_b32_e32 v4, 3, v32
	v_lshlrev_b32_e32 v2, 1, v2
	v_mov_b32_e32 v3, v151
	v_and_b32_e32 v25, 24, v4
	v_lshl_add_u64 v[2:3], s[4:5], 0, v[2:3]
	v_lshlrev_b32_e32 v4, 1, v25
	v_mov_b32_e32 v5, v151
	v_lshl_add_u64 v[16:17], v[2:3], 0, v[4:5]
	v_and_b32_e32 v2, 0xffffffe0, v22
	v_lshlrev_b32_e32 v6, 16, v7
	v_and_b32_e32 v7, 0xffff0000, v7
	v_lshlrev_b32_e32 v8, 16, v9
	v_and_b32_e32 v9, 0xffff0000, v9
	v_lshlrev_b32_e32 v26, 16, v10
	v_and_b32_e32 v27, 0xffff0000, v10
	v_lshlrev_b32_e32 v10, 16, v11
	v_and_b32_e32 v11, 0xffff0000, v11
	v_lshlrev_b32_e32 v28, 16, v12
	v_and_b32_e32 v29, 0xffff0000, v12
	v_lshlrev_b32_e32 v12, 16, v13
	v_and_b32_e32 v13, 0xffff0000, v13
	v_pk_mul_f32 v[18:19], v[18:19], s[6:7] op_sel_hi:[1,0]
	v_ashrrev_i32_e32 v3, 31, v2
	v_pk_mul_f32 v[20:21], v[20:21], s[6:7] op_sel_hi:[1,0]
	v_pk_mul_f32 v[6:7], v[6:7], s[6:7] op_sel_hi:[1,0]
	v_pk_mul_f32 v[8:9], v[8:9], s[6:7] op_sel_hi:[1,0]
	v_pk_mul_f32 v[26:27], v[26:27], s[6:7] op_sel_hi:[1,0]
	v_pk_mul_f32 v[10:11], v[10:11], s[6:7] op_sel_hi:[1,0]
	v_pk_mul_f32 v[28:29], v[28:29], s[6:7] op_sel_hi:[1,0]
	v_pk_mul_f32 v[12:13], v[12:13], s[6:7] op_sel_hi:[1,0]
	v_cvt_pk_bf16_f32 v114, v18, v19
	v_lshlrev_b64 v[18:19], 1, v[2:3]
	v_cvt_pk_bf16_f32 v116, v20, v21
	v_cvt_pk_bf16_f32 v119, v6, v7
	v_cvt_pk_bf16_f32 v121, v8, v9
	v_cvt_pk_bf16_f32 v122, v26, v27
	v_cvt_pk_bf16_f32 v123, v10, v11
	v_cvt_pk_bf16_f32 v124, v28, v29
	v_cvt_pk_bf16_f32 v125, v12, v13
	v_lshl_add_u64 v[10:11], v[16:17], 0, v[18:19]
	global_load_dwordx4 v[2:5], v[144:145], off offset:1024
	global_load_dwordx4 v[6:9], v[10:11], off offset:2048
	v_add_u32_e32 v10, 0x200, v32
	v_ashrrev_i32_e32 v10, 3, v10
	v_and_b32_e32 v10, 0xffffffe0, v10
	v_ashrrev_i32_e32 v11, 31, v10
	v_lshlrev_b64 v[20:21], 1, v[10:11]
	v_lshl_add_u64 v[10:11], v[16:17], 0, v[20:21]
	global_load_dwordx4 v[10:13], v[10:11], off offset:2048
	s_movk_i32 s6, 0x90
	v_mul_lo_u32 v15, v22, s6
	s_mov_b64 s[10:11], 0x65800
	v_and_b32_e32 v22, 0xfc0, v23
	v_and_b32_e32 v27, 48, v23
	v_add_u32_e32 v15, 0, v15
	v_and_b32_e32 v23, 0xfffff000, v23
	v_add3_u32 v22, 0, v22, v27
	v_add_u32_e32 v168, v15, v14
	v_lshl_add_u64 v[14:15], v[16:17], 0, s[10:11]
	v_add_u32_e32 v171, v22, v23
	v_lshl_add_u64 v[16:17], v[14:15], 0, v[18:19]
	v_add_co_u32_e32 v22, vcc, s8, v144
	v_lshl_add_u64 v[14:15], v[14:15], 0, v[20:21]
	s_nop 0
	v_addc_co_u32_e32 v23, vcc, 0, v145, vcc
	global_load_dwordx4 v[130:133], v[16:17], off
	global_load_dwordx4 v[134:137], v[14:15], off
	global_load_dwordx4 v[138:141], v[22:23], off offset:1024
	v_cvt_f32_i32_e32 v28, s3
	s_add_i32 s3, s46, s27
	v_lshrrev_b32_e32 v26, 2, v32
	s_waitcnt vmcnt(5)
; template <int DQK, int DV, bool BIAS> ...
;     ...
; #pragma unroll
;     for (int d = 0; d < NDT; ++d)
; #pragma unroll
;         for (int r = 0; r < 16; ++r) o[d][r] = 0.f;
; #pragma unroll
;     for (int ks = 0; ks < NKS; ++ks) asm volatile("" : "+v"(qf[ks]));
;     float mhat = 0.f, l = 0.f; f32x16 negm;
; #pragma unroll
;     for (int r = 0; r < 16; ++r) negm[r] = 0.f;
;     constexpr int TPB = (DV == 64) ? 2 : 1, NG = SEQL / 64 / TPB;
;     u32x4 kreg[TPB], k2reg[TPB], vreg[TPB][NVL];
;     const bf16_t* kptr = Kg + (size_t)(tid >> 3) * ldk + (tid & 7) * 8;
;     const bf16_t* k2ptr = (DQK == 96) ? K2g + (size_t)(tid >> 2) * ldk2 + (tid & 3) * 8 : nullptr;
;     ...
;     u32x4 pw[4];
; #pragma unroll
;     for (int j = 0; j < TPB; ++j) { ATT_LOAD(j, j); ATT_STORE(j, j); }
; #pragma unroll
;     for (int j = 0; j < TPB; ++j) ATT_LOAD(TPB + j, j);
;     const float qp = (float)(qpos0 + r32);
; __device__ __forceinline__ void attn_phase(PPtr P, int li, LAS unsigned char* lds, int vcu, int wave, int lane) {
;     ...
;         const float slope = __builtin_amdgcn_exp2f(-2.f * (float)(h + 1));
	ds_write_b128 v168, v[2:5]
	s_waitcnt vmcnt(4)
	ds_write_b128 v171, v[6:9] offset:18432
	s_waitcnt vmcnt(3)
	ds_write_b128 v171, v[10:13] offset:26624
	v_or_b32_e32 v2, s3, v33
	v_cvt_f32_i32_e32 v172, v2
	v_and_or_b32 v2, v26, 3, v173
	v_lshlrev_b32_e32 v3, 1, v32
	v_mad_u32_u24 v22, v33, s6, 0
	v_lshl_add_u32 v2, v2, 6, 0
	v_and_b32_e32 v3, 32, v3
	s_or_b32 s6, s49, s9
	v_exp_f32_e32 v27, v28
	v_add3_u32 v174, v2, v3, v25
	v_mov_b32_e32 v2, s6
	v_mov_b32_e32 v3, s48
	v_mad_u64_u32 v[2:3], s[6:7], v24, s7, v[2:3]
	v_and_b32_e32 v4, 3, v32
	v_lshl_or_b32 v2, v4, 4, v2
	v_lshl_add_u64 v[4:5], v[2:3], 0, v[20:21]
	v_lshl_add_u64 v[2:3], v[2:3], 0, v[18:19]
	v_mov_b32_e32 v16, v151
	v_mov_b32_e32 v17, v151
	v_mbcnt_lo_u32_b32 v18, -1, 0
	v_mul_f32_e32 v142, 0x3fb8aa3b, v27
	v_lshl_add_u64 v[146:147], s[16:17], 0, v[4:5]
	v_lshl_add_u64 v[148:149], s[16:17], 0, v[2:3]
	v_mov_b32_e32 v2, v151
	v_mov_b32_e32 v3, v151
	v_mov_b32_e32 v4, v151
	v_mov_b32_e32 v5, v151
	v_mov_b32_e32 v6, v151
	v_mov_b32_e32 v7, v151
	v_mov_b32_e32 v8, v151
	v_mov_b32_e32 v9, v151
	v_mov_b32_e32 v10, v151
	v_mov_b32_e32 v11, v151
	v_mov_b32_e32 v12, v151
	v_mov_b32_e32 v13, v151
	v_mov_b32_e32 v14, v151
	v_mov_b32_e32 v15, v151
	s_mov_b32 s10, -2.0
	v_add_u32_e32 v175, v22, v150
	v_mbcnt_hi_u32_b32 v170, -1, v18
	v_mov_b64_e32 v[32:33], v[16:17]
	v_mov_b64_e32 v[48:49], v[16:17]
	v_mov_b64_e32 v[64:65], v[16:17]
	v_mov_b32_e32 v143, v142
	s_mov_b64 s[6:7], 0
	s_mov_b32 s8, 0xc2000000
	s_mov_b32 s11, 0xc0400000
	v_mov_b64_e32 v[30:31], v[14:15]
	v_mov_b64_e32 v[28:29], v[12:13]
	v_mov_b64_e32 v[26:27], v[10:11]
	v_mov_b64_e32 v[24:25], v[8:9]
	v_mov_b64_e32 v[22:23], v[6:7]
	v_mov_b64_e32 v[20:21], v[4:5]
	v_mov_b64_e32 v[18:19], v[2:3]
	v_mov_b64_e32 v[46:47], v[14:15]
	v_mov_b64_e32 v[44:45], v[12:13]
	v_mov_b64_e32 v[42:43], v[10:11]
	v_mov_b64_e32 v[40:41], v[8:9]
	v_mov_b64_e32 v[38:39], v[6:7]
	v_mov_b64_e32 v[36:37], v[4:5]
	v_mov_b64_e32 v[34:35], v[2:3]
	v_mov_b64_e32 v[62:63], v[14:15]
	v_mov_b64_e32 v[60:61], v[12:13]
	v_mov_b64_e32 v[58:59], v[10:11]
	v_mov_b64_e32 v[56:57], v[8:9]
	v_mov_b64_e32 v[54:55], v[6:7]
	v_mov_b64_e32 v[52:53], v[4:5]
	v_mov_b64_e32 v[50:51], v[2:3]
	v_mbcnt_lo_u32_b32 v239, -1, 0
	v_mbcnt_hi_u32_b32 v239, -1, v239
	v_and_b32_e32 v238, 31, v239
	v_lshrrev_b32_e32 v237, 3, v238
	v_and_b32_e32 v236, 3, v238
	v_lshl_add_u32 v237, v237, 2, v236
	v_bfe_u32 v236, v238, 2, 1
	v_lshlrev_b32_e32 v236, 2, v236
	v_mov_b32_e32 v233, 0
	v_mov_b32_e32 v234, 0
	v_cmp_eq_u32_e64 s[98:99], 0, v237
	v_cndmask_b32_e64 v233, v233, 32, s[98:99]
	v_cndmask_b32_e64 v234, v234, 34, s[98:99]
	v_cmp_eq_u32_e64 s[98:99], 1, v237
	v_cndmask_b32_e64 v233, v233, 33, s[98:99]
	v_cndmask_b32_e64 v234, v234, 35, s[98:99]
	v_cmp_eq_u32_e64 s[98:99], 2, v237
	v_cndmask_b32_e64 v233, v233, 48, s[98:99]
	v_cndmask_b32_e64 v234, v234, 42, s[98:99]
	v_cmp_eq_u32_e64 s[98:99], 3, v237
	v_cndmask_b32_e64 v233, v233, 49, s[98:99]
	v_cndmask_b32_e64 v234, v234, 43, s[98:99]
	v_cmp_eq_u32_e64 s[98:99], 4, v237
	v_cndmask_b32_e64 v233, v233, 40, s[98:99]
	v_cndmask_b32_e64 v234, v234, 0, s[98:99]
	v_cmp_eq_u32_e64 s[98:99], 5, v237
	v_cndmask_b32_e64 v233, v233, 41, s[98:99]
	v_cndmask_b32_e64 v234, v234, 1, s[98:99]
	v_cmp_eq_u32_e64 s[98:99], 6, v237
	v_cndmask_b32_e64 v233, v233, 50, s[98:99]
	v_cndmask_b32_e64 v234, v234, 16, s[98:99]
	v_cmp_eq_u32_e64 s[98:99], 7, v237
	v_cndmask_b32_e64 v233, v233, 51, s[98:99]
	v_cndmask_b32_e64 v234, v234, 17, s[98:99]
	v_cmp_eq_u32_e64 s[98:99], 8, v237
	v_cndmask_b32_e64 v233, v233, 56, s[98:99]
	v_cndmask_b32_e64 v234, v234, 2, s[98:99]
	v_cmp_eq_u32_e64 s[98:99], 9, v237
	v_cndmask_b32_e64 v233, v233, 57, s[98:99]
	v_cndmask_b32_e64 v234, v234, 3, s[98:99]
	v_cmp_eq_u32_e64 s[98:99], 10, v237
	v_cndmask_b32_e64 v233, v233, 58, s[98:99]
	v_cndmask_b32_e64 v234, v234, 18, s[98:99]
	v_cmp_eq_u32_e64 s[98:99], 11, v237
	v_cndmask_b32_e64 v233, v233, 59, s[98:99]
	v_cndmask_b32_e64 v234, v234, 19, s[98:99]
	v_cmp_eq_u32_e64 s[98:99], 12, v237
	v_cndmask_b32_e64 v233, v233, 24, s[98:99]
	v_cndmask_b32_e64 v234, v234, 8, s[98:99]
	v_cmp_eq_u32_e64 s[98:99], 13, v237
	v_cndmask_b32_e64 v233, v233, 25, s[98:99]
	v_cndmask_b32_e64 v234, v234, 9, s[98:99]
	v_cmp_eq_u32_e64 s[98:99], 14, v237
	v_cndmask_b32_e64 v233, v233, 26, s[98:99]
	v_cndmask_b32_e64 v234, v234, 10, s[98:99]
	v_cmp_eq_u32_e64 s[98:99], 15, v237
	v_cndmask_b32_e64 v233, v233, 27, s[98:99]
	v_cndmask_b32_e64 v234, v234, 11, s[98:99]
	v_add_u32_e32 v233, v233, v236
	v_add_u32_e32 v234, v234, v236
	v_mul_u32_u24_e32 v235, 0x90, v238
	v_mul_u32_u24_e32 v240, 0x90, v233
	v_mul_u32_u24_e32 v241, 0x90, v234
	v_sub_u32_e32 v240, v240, v235
	v_sub_u32_e32 v241, v241, v235
	v_add_u32_e32 v240, v240, v175
	v_add_u32_e32 v241, v241, v175
	v_cvt_f32_u32_e32 v233, v233
	v_cvt_f32_u32_e32 v234, v234
	v_mul_f32_e32 v233, v142, v233
	v_mul_f32_e32 v234, v142, v234
	v_cmp_gt_u32_e64 s[98:99], 32, v239
	v_cndmask_b32_e64 v242, v233, 1.0, s[98:99]
	v_cndmask_b32_e64 v243, v234, 1.0, s[98:99]
	v_xor_b32_e32 v233, 0x80000000, v233
	v_xor_b32_e32 v234, 0x80000000, v234
	v_cndmask_b32_e64 v244, v233, 1.0, s[98:99]
	v_cndmask_b32_e64 v245, v234, 1.0, s[98:99]
	v_xor_b32_e32 v231, 0x80000000, v142
	v_cndmask_b32_e64 v231, 0, v231, s[98:99]
	v_cndmask_b32_e64 v232, 1.0, 0, s[98:99]
	s_branch .LBB0_576

; #define LAS __attribute__((address_space(3)))
; template <int DQK, int DV, bool BIAS> ...
;     ...
;       for (int sub = 0; sub < TPB; ++sub) {
;         const int t = g * TPB + sub, buf = pair * TPB + sub, vcur = buf;
;         f32x16 p0, p1;
;         const LAS unsigned char* kb = lds + buf * KBUF + r32 * KP + hi * 16;
; #pragma unroll
;         for (int ks = 0; ks < NKS; ++ks) {
;             const bf16x8 k0 = *(const LAS bf16x8*)(kb + ks * 32), k1 = *(const LAS bf16x8*)(kb + 32 * KP + ks * 32);
;             if (ks == 0) { p0 = __builtin_amdgcn_mfma_f32_32x32x16_bf16(k0, qf[0], negm, 0, 0, 0); p1 = __builtin_amdgcn_mfma_f32_32x32x16_bf16(k1, qf[0], negm, 0, 0, 0); }
;             else { p0 = __builtin_amdgcn_mfma_f32_32x32x16_bf16(k0, qf[ks], p0, 0, 0, 0); p1 = __builtin_amdgcn_mfma_f32_32x32x16_bf16(k1, qf[ks], p1, 0, 0, 0); }
;         }
;         if (BIAS) {
;             asm volatile("s_nop 15\n\ts_nop 7" : "+v"(p0), "+v"(p1));
;             const float d0 = qp - (float)(t * 64 + 4 * hi);
; #pragma unroll
;             for (int r = 0; r < 16; ++r) { const float dk = d0 - (float)((r & 3) + 8 * (r >> 2)); p0[r] = p0[r] - sl2 * fabsf(dk); p1[r] = p1[r] - sl2 * fabsf(dk - 32.f); }
;         } else {
;             asm volatile("s_nop 15\n\ts_nop 7" : "+v"(p0), "+v"(p1));
;         }
.LBB0_578:
	ds_read_b128 v[82:85], v240
	ds_read_b128 v[86:89], v240 offset:32
	ds_read_b128 v[90:93], v241
	ds_read_b128 v[94:97], v241 offset:32
	v_cvt_f32_u32_e32 v150, v173
	s_waitcnt lgkmcnt(3)
	v_mfma_f32_32x32x16_bf16 v[98:113], v[82:85], v[114:117], v[66:81]
	v_sub_f32_e32 v178, v172, v150
	s_waitcnt lgkmcnt(1)
	v_mfma_f32_32x32x16_bf16 v[152:167], v[90:93], v[114:117], v[66:81]
	v_mfma_f32_32x32x16_bf16 v[98:113], v[86:89], v[118:121], v[98:113]
	ds_read_b128 v[82:85], v240 offset:64
	ds_read_b128 v[86:89], v240 offset:96
	s_waitcnt lgkmcnt(2)
	v_mfma_f32_32x32x16_bf16 v[152:167], v[94:97], v[118:121], v[152:167]
	s_waitcnt lgkmcnt(1)
	v_mfma_f32_32x32x16_bf16 v[98:113], v[82:85], v[122:125], v[98:113]
	ds_read_b128 v[90:93], v241 offset:64
	ds_read_b128 v[94:97], v241 offset:96
	s_waitcnt lgkmcnt(1)
	v_mfma_f32_32x32x16_bf16 v[152:167], v[90:93], v[122:125], v[152:167]
	v_mfma_f32_32x32x16_bf16 v[98:113], v[86:89], v[126:129], v[98:113]
	s_waitcnt lgkmcnt(0)
	v_mfma_f32_32x32x16_bf16 v[152:167], v[94:97], v[126:129], v[152:167]
	v_readfirstlane_b32 s98, v178
	s_nop 8
	s_cmp_lt_i32 s98, 0
	s_cbranch_scc1 .Lfb1_r
	s_cmp_lt_u32 s98, 0x42800000
	s_cbranch_scc1 .Lfb1_d
	v_fma_f32 v230, v231, v178, v232
	s_nop 1
	v_mfma_f32_32x32x2_f32 v[98:113], v242, v230, v[98:113]
	v_mfma_f32_32x32x2_f32 v[152:167], v243, v230, v[152:167]
	s_branch .Lfb1_j
.Lfb1_r:
	v_fma_f32 v230, -v231, v178, v232
	s_nop 1
	v_mfma_f32_32x32x2_f32 v[98:113], v244, v230, v[98:113]
	v_mfma_f32_32x32x2_f32 v[152:167], v245, v230, v[152:167]
.Lfb1_j:
	s_nop 15
	s_nop 3
	s_branch .Lfb1_m
.Lfb1_d:
	s_nop 7
	v_add_f32_e32 v239, 0xc2000000, v178
	v_fma_f32 v98, -v142, |v239|, v98
	v_add_f32_e32 v239, 0xc2040000, v178
	v_fma_f32 v99, -v142, |v239|, v99
	v_add_f32_e32 v239, 0xc2400000, v178
	v_fma_f32 v100, -v142, |v239|, v100
	v_add_f32_e32 v239, 0xc2440000, v178
	v_fma_f32 v101, -v142, |v239|, v101
	v_add_f32_e32 v239, 0xc2200000, v178
	v_fma_f32 v102, -v142, |v239|, v102
	v_add_f32_e32 v239, 0xc2240000, v178
	v_fma_f32 v103, -v142, |v239|, v103
	v_add_f32_e32 v239, 0xc2480000, v178
	v_fma_f32 v104, -v142, |v239|, v104
	v_add_f32_e32 v239, 0xc24c0000, v178
	v_fma_f32 v105, -v142, |v239|, v105
	v_add_f32_e32 v239, 0xc2600000, v178
	v_fma_f32 v106, -v142, |v239|, v106
	v_add_f32_e32 v239, 0xc2640000, v178
	v_fma_f32 v107, -v142, |v239|, v107
	v_add_f32_e32 v239, 0xc2680000, v178
	v_fma_f32 v108, -v142, |v239|, v108
	v_add_f32_e32 v239, 0xc26c0000, v178
	v_fma_f32 v109, -v142, |v239|, v109
	v_add_f32_e32 v239, 0xc1c00000, v178
	v_fma_f32 v110, -v142, |v239|, v110
	v_add_f32_e32 v239, 0xc1c80000, v178
	v_fma_f32 v111, -v142, |v239|, v111
	v_add_f32_e32 v239, 0xc1d00000, v178
	v_fma_f32 v112, -v142, |v239|, v112
	v_add_f32_e32 v239, 0xc1d80000, v178
	v_fma_f32 v113, -v142, |v239|, v113
	v_add_f32_e32 v239, 0xc2080000, v178
	v_fma_f32 v152, -v142, |v239|, v152
	v_add_f32_e32 v239, 0xc20c0000, v178
	v_fma_f32 v153, -v142, |v239|, v153
	v_add_f32_e32 v239, 0xc2280000, v178
	v_fma_f32 v154, -v142, |v239|, v154
	v_add_f32_e32 v239, 0xc22c0000, v178
	v_fma_f32 v155, -v142, |v239|, v155
	v_fma_f32 v156, -v142, |v178|, v156
	v_add_f32_e32 v239, 0xbf800000, v178
	v_fma_f32 v157, -v142, |v239|, v157
	v_add_f32_e32 v239, 0xc1800000, v178
	v_fma_f32 v158, -v142, |v239|, v158
	v_add_f32_e32 v239, 0xc1880000, v178
	v_fma_f32 v159, -v142, |v239|, v159
	v_add_f32_e32 v239, 0xc0000000, v178
	v_fma_f32 v160, -v142, |v239|, v160
	v_add_f32_e32 v239, 0xc0400000, v178
	v_fma_f32 v161, -v142, |v239|, v161
	v_add_f32_e32 v239, 0xc1900000, v178
	v_fma_f32 v162, -v142, |v239|, v162
	v_add_f32_e32 v239, 0xc1980000, v178
	v_fma_f32 v163, -v142, |v239|, v163
	v_add_f32_e32 v239, 0xc1000000, v178
	v_fma_f32 v164, -v142, |v239|, v164
	v_add_f32_e32 v239, 0xc1100000, v178
	v_fma_f32 v165, -v142, |v239|, v165
	v_add_f32_e32 v239, 0xc1200000, v178
	v_fma_f32 v166, -v142, |v239|, v166
	v_add_f32_e32 v239, 0xc1300000, v178
	v_fma_f32 v167, -v142, |v239|, v167
; __device__ __forceinline__ float max3f(float a, float b, float c) { float r; asm("v_max3_f32 %0, %1, %2, %3" : "=v"(r) : "v"(a), "v"(b), "v"(c)); return r; }
; template <int DQK, int DV, bool BIAS> ...
;     ...
;         float mxa = max3f(p0[0], p0[1], p1[0]), mxb = max3f(p0[2], p0[3], p1[1]); mxa = max3f(mxa, p1[2], p1[3]);
; #pragma unroll
;         for (int r = 4; r < 16; r += 4) { mxa = max3f(mxa, p0[r], p0[r + 1]); mxb = max3f(mxb, p0[r + 2], p0[r + 3]); mxa = max3f(mxa, p1[r], p1[r + 1]); mxb = max3f(mxb, p1[r + 2], p1[r + 3]); }
;         float mx = fmaxf(mxa, mxb);
;         if (__any(mx > 8.f)) {
;             mx = fmaxf(mx, __shfl_xor(mx, 32));
;             const float dl = fmaxf(mx, 0.f); mhat += dl;
;             const float f = __builtin_amdgcn_exp2f(-dl);
; #pragma unroll
;             for (int r = 0; r < 16; ++r) { p0[r] -= dl; p1[r] -= dl; negm[r] = -mhat; }
;             l *= f;
; #pragma unroll
;             for (int d = 0; d < NDT; ++d)
; #pragma unroll
;                 for (int r = 0; r < 16; ++r) o[d][r] *= f;
;         }
.Lfb1_m:
	v_max3_f32 v82, v156, v157, v98
	v_max3_f32 v83, v160, v161, v99
	v_max3_f32 v82, v82, v152, v153
	v_max3_f32 v83, v83, v166, v167
	v_max3_f32 v82, v82, v164, v165
	v_max3_f32 v83, v83, v154, v155
	v_max3_f32 v82, v82, v102, v103
	v_max3_f32 v83, v83, v162, v163
	v_max3_f32 v82, v82, v158, v159
	v_max3_f32 v83, v83, v104, v105
	v_max3_f32 v82, v82, v100, v101
	v_max3_f32 v83, v83, v112, v113
	v_max3_f32 v82, v82, v110, v111
	v_max3_f32 v83, v83, v108, v109
	v_max3_f32 v82, v82, v106, v107
	v_max_f32_e32 v82, v82, v83
	v_cmp_gt_f32_e32 vcc, 0xc3400000, v82
	s_cmp_eq_u64 vcc, exec
	s_cbranch_scc1 .Lsk1_p4a1
	v_cmp_lt_f32_e32 vcc, s52, v82
	s_cbranch_vccz .LBB0_580
	v_and_b32_e32 v67, 64, v170
	v_xor_b32_e32 v66, 32, v170
	v_add_u32_e32 v67, 64, v67
	v_cmp_lt_i32_e32 vcc, v66, v67
	s_nop 1
	v_cndmask_b32_e32 v66, v170, v66, vcc
	v_lshlrev_b32_e32 v66, 2, v66
	ds_bpermute_b32 v66, v66, v82
	s_waitcnt lgkmcnt(0)
	v_max3_f32 v67, v82, v66, 0
	v_exp_f32_e64 v66, -v67
	v_add_f32_e32 v176, v176, v67
	v_xor_b32_e32 v82, 0x80000000, v176
	v_sub_f32_e32 v98, v98, v67
	v_sub_f32_e32 v99, v99, v67
	v_sub_f32_e32 v152, v152, v67
	v_sub_f32_e32 v153, v153, v67
	v_sub_f32_e32 v102, v102, v67
	v_sub_f32_e32 v103, v103, v67
	v_sub_f32_e32 v154, v154, v67
	v_sub_f32_e32 v155, v155, v67
	v_sub_f32_e32 v100, v100, v67
	v_sub_f32_e32 v101, v101, v67
	v_sub_f32_e32 v104, v104, v67
	v_sub_f32_e32 v105, v105, v67
	v_sub_f32_e32 v106, v106, v67
	v_sub_f32_e32 v107, v107, v67
	v_sub_f32_e32 v108, v108, v67
	v_sub_f32_e32 v109, v109, v67
	v_pk_mul_f32 v[64:65], v[64:65], v[66:67] op_sel_hi:[1,0]
	v_pk_mul_f32 v[62:63], v[62:63], v[66:67] op_sel_hi:[1,0]
	v_pk_mul_f32 v[60:61], v[60:61], v[66:67] op_sel_hi:[1,0]
	v_pk_mul_f32 v[58:59], v[58:59], v[66:67] op_sel_hi:[1,0]
	v_pk_mul_f32 v[56:57], v[56:57], v[66:67] op_sel_hi:[1,0]
	v_pk_mul_f32 v[54:55], v[54:55], v[66:67] op_sel_hi:[1,0]
	v_pk_mul_f32 v[52:53], v[52:53], v[66:67] op_sel_hi:[1,0]
	v_pk_mul_f32 v[50:51], v[50:51], v[66:67] op_sel_hi:[1,0]
	v_pk_mul_f32 v[48:49], v[48:49], v[66:67] op_sel_hi:[1,0]
	v_pk_mul_f32 v[46:47], v[46:47], v[66:67] op_sel_hi:[1,0]
	v_pk_mul_f32 v[44:45], v[44:45], v[66:67] op_sel_hi:[1,0]
	v_pk_mul_f32 v[42:43], v[42:43], v[66:67] op_sel_hi:[1,0]
	v_pk_mul_f32 v[40:41], v[40:41], v[66:67] op_sel_hi:[1,0]
	v_pk_mul_f32 v[38:39], v[38:39], v[66:67] op_sel_hi:[1,0]
	v_pk_mul_f32 v[36:37], v[36:37], v[66:67] op_sel_hi:[1,0]
	v_pk_mul_f32 v[34:35], v[34:35], v[66:67] op_sel_hi:[1,0]
	v_pk_mul_f32 v[32:33], v[32:33], v[66:67] op_sel_hi:[1,0]
	v_pk_mul_f32 v[30:31], v[30:31], v[66:67] op_sel_hi:[1,0]
	v_pk_mul_f32 v[28:29], v[28:29], v[66:67] op_sel_hi:[1,0]
	v_pk_mul_f32 v[26:27], v[26:27], v[66:67] op_sel_hi:[1,0]
	v_pk_mul_f32 v[24:25], v[24:25], v[66:67] op_sel_hi:[1,0]
	v_pk_mul_f32 v[22:23], v[22:23], v[66:67] op_sel_hi:[1,0]
	v_pk_mul_f32 v[20:21], v[20:21], v[66:67] op_sel_hi:[1,0]
	v_pk_mul_f32 v[18:19], v[18:19], v[66:67] op_sel_hi:[1,0]
	v_pk_mul_f32 v[16:17], v[16:17], v[66:67] op_sel_hi:[1,0]
	v_pk_mul_f32 v[14:15], v[14:15], v[66:67] op_sel_hi:[1,0]
	v_pk_mul_f32 v[12:13], v[12:13], v[66:67] op_sel_hi:[1,0]
	v_pk_mul_f32 v[10:11], v[10:11], v[66:67] op_sel_hi:[1,0]
	v_pk_mul_f32 v[8:9], v[8:9], v[66:67] op_sel_hi:[1,0]
	v_pk_mul_f32 v[6:7], v[6:7], v[66:67] op_sel_hi:[1,0]
	v_pk_mul_f32 v[4:5], v[4:5], v[66:67] op_sel_hi:[1,0]
	v_pk_mul_f32 v[2:3], v[2:3], v[66:67] op_sel_hi:[1,0]
	v_sub_f32_e32 v156, v156, v67
	v_sub_f32_e32 v157, v157, v67
	v_sub_f32_e32 v160, v160, v67
	v_sub_f32_e32 v161, v161, v67
	v_sub_f32_e32 v164, v164, v67
	v_sub_f32_e32 v165, v165, v67
	v_sub_f32_e32 v166, v166, v67
	v_sub_f32_e32 v167, v167, v67
	v_sub_f32_e32 v158, v158, v67
	v_sub_f32_e32 v159, v159, v67
	v_sub_f32_e32 v162, v162, v67
	v_sub_f32_e32 v163, v163, v67
	v_sub_f32_e32 v110, v110, v67
	v_sub_f32_e32 v111, v111, v67
	v_sub_f32_e32 v112, v112, v67
	v_sub_f32_e32 v113, v113, v67
	v_mul_f32_e32 v151, v151, v66
	v_mov_b32_e32 v66, v82
	v_mov_b32_e32 v67, v82
	v_mov_b32_e32 v68, v82
	v_mov_b32_e32 v69, v82
	v_mov_b32_e32 v70, v82
	v_mov_b32_e32 v71, v82
	v_mov_b32_e32 v72, v82
	v_mov_b32_e32 v73, v82
	v_mov_b32_e32 v74, v82
	v_mov_b32_e32 v75, v82
	v_mov_b32_e32 v76, v82
	v_mov_b32_e32 v77, v82
	v_mov_b32_e32 v78, v82
	v_mov_b32_e32 v79, v82
	v_mov_b32_e32 v80, v82
	v_mov_b32_e32 v81, v82
	s_branch .LBB0_581

; #define LAS __attribute__((address_space(3)))
; __device__ __forceinline__ unsigned cvtpk(float lo, float hi) { typedef __bf16 bf2 __attribute__((ext_vector_type(2))); f32x2 v = {lo, hi}; bf2 b = __builtin_convertvector(v, bf2); return __builtin_bit_cast(unsigned, b); }
; template <int DQK, int DV, bool BIAS> ...
;     ...
;     __syncthreads();
;     ...
;     l += __shfl_xor(l, 32);
;     const float inv = 1.f / l;
; #pragma unroll
;     for (int d = 0; d < NDT; ++d)
; #pragma unroll
;         for (int r = 0; r < 16; ++r) o[d][r] *= inv;
; }
; __device__ __forceinline__ void attn_phase(PPtr P, int li, LAS unsigned char* lds, int vcu, int wave, int lane) {
;     ...
;         LAS unsigned* o1s = (LAS unsigned*)(lds + 81920 + wave * 8192) + lane;
; #pragma unroll
;         for (int d = 0; d < 4; ++d)
; #pragma unroll
;             for (int r = 0; r < 8; ++r) o1s[(d * 8 + r) * 64] = cvtpk(o1[d][2 * r], o1[d][2 * r + 1]);
;         attn_pass<64, 128, true>(lds, proj + qrow * LDP + C_AQ + h * 128 + 64, LDP, nullptr, 0, proj + seq0 * LDP + C_AK + h * 128 + 64, LDP, nullptr, 0, proj + seq0 * LDP + C_AV + h * 128, LDP, qb * 256 + wave * 32, 0.125f * LOG2E, slope * LOG2E, nullptr, o2);
.LBB0_586:
	v_and_b32_e32 v67, 64, v170
	v_xor_b32_e32 v66, 32, v170
	v_add_u32_e32 v172, 64, v67
	v_cmp_lt_i32_e32 vcc, v66, v172
	v_and_b32_e32 v173, 63, v169
	s_nop 0
	v_cndmask_b32_e32 v66, v170, v66, vcc
	v_lshlrev_b32_e32 v168, 2, v66
	ds_bpermute_b32 v66, v168, v151
	s_barrier
	s_waitcnt lgkmcnt(0)
	s_movk_i32 s8, 0x1940
	s_mov_b32 s10, 0xc1000000
	v_add_f32_e32 v66, v151, v66
	v_div_scale_f32 v67, s[6:7], v66, v66, 1.0
	v_rcp_f32_e32 v68, v67
	s_lshl_b32 s6, s50, 13
	s_add_i32 s6, s6, 0
	v_mov_b32_e32 v151, 0
	v_fma_f32 v69, -v67, v68, 1.0
	v_fmac_f32_e32 v68, v69, v68
	v_div_scale_f32 v69, vcc, 1.0, v66, 1.0
	v_mul_f32_e32 v70, v69, v68
	v_fma_f32 v71, -v67, v70, v69
	v_fmac_f32_e32 v70, v71, v68
	v_fma_f32 v67, -v67, v70, v69
	v_div_fmas_f32 v67, v67, v68, v70
	v_div_fixup_f32 v66, v67, v66, 1.0
	v_pk_mul_f32 v[50:51], v[50:51], v[66:67] op_sel_hi:[1,0]
	v_pk_mul_f32 v[52:53], v[52:53], v[66:67] op_sel_hi:[1,0]
	v_pk_mul_f32 v[54:55], v[54:55], v[66:67] op_sel_hi:[1,0]
	v_pk_mul_f32 v[56:57], v[56:57], v[66:67] op_sel_hi:[1,0]
	v_pk_mul_f32 v[58:59], v[58:59], v[66:67] op_sel_hi:[1,0]
	v_pk_mul_f32 v[60:61], v[60:61], v[66:67] op_sel_hi:[1,0]
	v_pk_mul_f32 v[62:63], v[62:63], v[66:67] op_sel_hi:[1,0]
	v_pk_mul_f32 v[64:65], v[64:65], v[66:67] op_sel_hi:[1,0]
	v_pk_mul_f32 v[34:35], v[34:35], v[66:67] op_sel_hi:[1,0]
	v_pk_mul_f32 v[36:37], v[36:37], v[66:67] op_sel_hi:[1,0]
	v_pk_mul_f32 v[38:39], v[38:39], v[66:67] op_sel_hi:[1,0]
	v_pk_mul_f32 v[40:41], v[40:41], v[66:67] op_sel_hi:[1,0]
	v_pk_mul_f32 v[42:43], v[42:43], v[66:67] op_sel_hi:[1,0]
	v_pk_mul_f32 v[44:45], v[44:45], v[66:67] op_sel_hi:[1,0]
	v_pk_mul_f32 v[46:47], v[46:47], v[66:67] op_sel_hi:[1,0]
	v_pk_mul_f32 v[48:49], v[48:49], v[66:67] op_sel_hi:[1,0]
	v_pk_mul_f32 v[18:19], v[18:19], v[66:67] op_sel_hi:[1,0]
	v_pk_mul_f32 v[20:21], v[20:21], v[66:67] op_sel_hi:[1,0]
	v_pk_mul_f32 v[22:23], v[22:23], v[66:67] op_sel_hi:[1,0]
	v_pk_mul_f32 v[24:25], v[24:25], v[66:67] op_sel_hi:[1,0]
	v_pk_mul_f32 v[26:27], v[26:27], v[66:67] op_sel_hi:[1,0]
	v_pk_mul_f32 v[28:29], v[28:29], v[66:67] op_sel_hi:[1,0]
	v_pk_mul_f32 v[30:31], v[30:31], v[66:67] op_sel_hi:[1,0]
	v_pk_mul_f32 v[32:33], v[32:33], v[66:67] op_sel_hi:[1,0]
	v_pk_mul_f32 v[2:3], v[2:3], v[66:67] op_sel_hi:[1,0]
	v_pk_mul_f32 v[4:5], v[4:5], v[66:67] op_sel_hi:[1,0]
	v_pk_mul_f32 v[6:7], v[6:7], v[66:67] op_sel_hi:[1,0]
	v_pk_mul_f32 v[8:9], v[8:9], v[66:67] op_sel_hi:[1,0]
	v_pk_mul_f32 v[10:11], v[10:11], v[66:67] op_sel_hi:[1,0]
	v_pk_mul_f32 v[12:13], v[12:13], v[66:67] op_sel_hi:[1,0]
	v_pk_mul_f32 v[14:15], v[14:15], v[66:67] op_sel_hi:[1,0]
	v_pk_mul_f32 v[16:17], v[16:17], v[66:67] op_sel_hi:[1,0]
	v_lshl_add_u32 v66, v173, 2, s6
	v_add_u32_e32 v171, 0x14000, v66
	v_cvt_pk_bf16_f32 v50, v50, v51
	v_cvt_pk_bf16_f32 v51, v52, v53
	v_cvt_pk_bf16_f32 v34, v34, v35
	v_cvt_pk_bf16_f32 v35, v36, v37
	v_cvt_pk_bf16_f32 v18, v18, v19
	v_cvt_pk_bf16_f32 v19, v20, v21
	v_cvt_pk_bf16_f32 v2, v2, v3
	v_cvt_pk_bf16_f32 v3, v4, v5
	ds_write2st64_b32 v171, v50, v51 offset1:1
	v_cvt_pk_bf16_f32 v50, v54, v55
	v_cvt_pk_bf16_f32 v51, v56, v57
	ds_write2st64_b32 v171, v34, v35 offset0:8 offset1:9
	v_cvt_pk_bf16_f32 v34, v38, v39
	v_cvt_pk_bf16_f32 v35, v40, v41
	ds_write2st64_b32 v171, v18, v19 offset0:16 offset1:17
	v_cvt_pk_bf16_f32 v18, v22, v23
	v_cvt_pk_bf16_f32 v19, v24, v25
	ds_write2st64_b32 v171, v2, v3 offset0:24 offset1:25
	v_cvt_pk_bf16_f32 v2, v6, v7
	v_cvt_pk_bf16_f32 v3, v8, v9
	ds_write2st64_b32 v171, v50, v51 offset0:2 offset1:3
	v_cvt_pk_bf16_f32 v50, v58, v59
	v_cvt_pk_bf16_f32 v51, v60, v61
	ds_write2st64_b32 v171, v34, v35 offset0:10 offset1:11
	v_cvt_pk_bf16_f32 v34, v42, v43
	v_cvt_pk_bf16_f32 v35, v44, v45
	ds_write2st64_b32 v171, v18, v19 offset0:18 offset1:19
	v_cvt_pk_bf16_f32 v18, v26, v27
	v_cvt_pk_bf16_f32 v19, v28, v29
	ds_write2st64_b32 v171, v2, v3 offset0:26 offset1:27
	v_cvt_pk_bf16_f32 v2, v10, v11
	v_cvt_pk_bf16_f32 v3, v12, v13
	ds_write2st64_b32 v171, v50, v51 offset0:4 offset1:5
	v_cvt_pk_bf16_f32 v50, v62, v63
	v_cvt_pk_bf16_f32 v51, v64, v65
	ds_write2st64_b32 v171, v34, v35 offset0:12 offset1:13
	v_cvt_pk_bf16_f32 v34, v46, v47
	v_cvt_pk_bf16_f32 v35, v48, v49
	ds_write2st64_b32 v171, v18, v19 offset0:20 offset1:21
	v_cvt_pk_bf16_f32 v18, v30, v31
	v_cvt_pk_bf16_f32 v19, v32, v33
	ds_write2st64_b32 v171, v2, v3 offset0:28 offset1:29
	v_cvt_pk_bf16_f32 v2, v14, v15
	v_cvt_pk_bf16_f32 v3, v16, v17
	v_mov_b32_e32 v22, v1
	ds_write2st64_b32 v171, v50, v51 offset0:6 offset1:7
	ds_write2st64_b32 v171, v34, v35 offset0:14 offset1:15
	ds_write2st64_b32 v171, v18, v19 offset0:22 offset1:23
	ds_write2st64_b32 v171, v2, v3 offset0:30 offset1:31
	s_mov_b32 s6, 0x3e38aa3b
	v_and_b32_e32 v23, 31, v22
	v_mul_u32_u24_e32 v2, 0xca0, v23
	v_bfe_u32 v24, v22, 5, 1
	v_lshlrev_b32_e32 v150, 1, v2
	v_lshl_add_u64 v[2:3], s[18:19], 0, v[150:151]
	v_lshlrev_b32_e32 v150, 4, v24
	v_lshl_add_u64 v[18:19], v[2:3], 0, v[150:151]
	global_load_dwordx4 v[2:5], v[18:19], off offset:128
	global_load_dwordx4 v[6:9], v[18:19], off offset:160
	global_load_dwordx4 v[10:13], v[18:19], off offset:192
	global_load_dwordx4 v[14:17], v[18:19], off offset:224
	v_ashrrev_i32_e32 v25, 3, v22
	v_lshlrev_b32_e32 v26, 4, v22
	v_lshrrev_b32_e32 v28, 2, v22
	v_lshlrev_b32_e32 v177, 2, v24
	v_and_b32_e32 v29, 0xfc0, v26
	v_and_b32_e32 v30, 48, v26
	v_mov_b32_e32 v50, v151
	v_mov_b32_e32 v51, v151
	v_mov_b32_e32 v52, v151
	v_mov_b32_e32 v53, v151
	v_mov_b32_e32 v54, v151
	v_mov_b32_e32 v55, v151
	v_mov_b32_e32 v56, v151
	v_mov_b32_e32 v57, v151
	v_mov_b32_e32 v58, v151
	v_mov_b32_e32 v59, v151
	v_mov_b32_e32 v60, v151
	v_mov_b32_e32 v61, v151
	v_mov_b32_e32 v62, v151
	v_mov_b32_e32 v63, v151
	v_mov_b32_e32 v64, v151
	v_mov_b32_e32 v65, v151
	s_mov_b32 s22, 0xc1200000
	s_mov_b32 s34, 0xc1800000
	s_mov_b32 s36, 0xc1900000
	s_mov_b32 s38, 0xc1c00000
	s_mov_b32 s40, 0xc1d00000
	v_mov_b64_e32 v[34:35], v[50:51]
	s_mov_b32 s11, 0xc1100000
	s_mov_b32 s23, 0xc1300000
	s_mov_b32 s35, 0xc1880000
	s_mov_b32 s37, 0xc1980000
	s_mov_b32 s39, 0xc1c80000
	s_mov_b32 s41, 0xc1d80000
	s_mov_b32 s44, 0x41000000
	v_mov_b64_e32 v[36:37], v[52:53]
	v_mov_b64_e32 v[38:39], v[54:55]
	v_mov_b64_e32 v[40:41], v[56:57]
	v_mov_b64_e32 v[42:43], v[58:59]
	v_mov_b64_e32 v[44:45], v[60:61]
	v_mov_b64_e32 v[46:47], v[62:63]
	v_mov_b64_e32 v[48:49], v[64:65]
	v_mov_b32_e32 v180, v151
	v_mov_b32_e32 v66, v151
	v_mov_b32_e32 v67, v151
	v_mov_b32_e32 v68, v151
	v_mov_b32_e32 v69, v151
	v_mov_b32_e32 v70, v151
	v_mov_b32_e32 v71, v151
	v_mov_b32_e32 v72, v151
	v_mov_b32_e32 v73, v151
	v_mov_b32_e32 v74, v151
	v_mov_b32_e32 v75, v151
	v_mov_b32_e32 v76, v151
	v_mov_b32_e32 v77, v151
	v_mov_b32_e32 v78, v151
	v_mov_b32_e32 v79, v151
	v_mov_b32_e32 v80, v151
	v_mov_b32_e32 v81, v151
	s_waitcnt vmcnt(3)
; __device__ __forceinline__ unsigned cvtpk(float lo, float hi) { typedef __bf16 bf2 __attribute__((ext_vector_type(2))); f32x2 v = {lo, hi}; bf2 b = __builtin_convertvector(v, bf2); return __builtin_bit_cast(unsigned, b); }
; template <int DQK, int DV, bool BIAS> ...
;     ...
;     for (int ks = 0; ks < NKS; ++ks) qf[ks] = ks < 4 ? *(const bf16x8*)(Qw + (size_t)r32 * ldq + ks * 16 + hi * 8) : *(const bf16x8*)(Q2w + (size_t)r32 * ldq2 + (ks - 4) * 16 + hi * 8);
; #pragma unroll
;     for (int ks = 0; ks < 4; ++ks) qf[ks] = scale_frag(qf[ks], cs);
;     if constexpr (DQK == 96) {
;         const float* rp = ropetab + ((size_t)(qpos0 + r32) * 16) * 2;
; #pragma unroll
;         for (int ks = 4; ks < 6; ++ks) {
;             const f32x4 c0 = *(const f32x4*)(rp + ((ks - 4) * 8 + hi * 4) * 2), c1 = *(const f32x4*)(rp + ((ks - 4) * 8 + hi * 4 + 2) * 2);
;             const u32x4 w = __builtin_bit_cast(u32x4, qf[ks]); u32x4 ow;
;             { const float a = bflo(w.x) * cs, b = bfhi(w.x) * cs; ow.x = cvtpk(a * c0[0] - b * c0[1], a * c0[1] + b * c0[0]); }
;             { const float a = bflo(w.y) * cs, b = bfhi(w.y) * cs; ow.y = cvtpk(a * c0[2] - b * c0[3], a * c0[3] + b * c0[2]); }
;             { const float a = bflo(w.z) * cs, b = bfhi(w.z) * cs; ow.z = cvtpk(a * c1[0] - b * c1[1], a * c1[1] + b * c1[0]); }
;             { const float a = bflo(w.w) * cs, b = bfhi(w.w) * cs; ow.w = cvtpk(a * c1[2] - b * c1[3], a * c1[3] + b * c1[2]); }
;             qf[ks] = __builtin_bit_cast(bf16x8, ow);
;         }
;     }
; #pragma unroll
;     for (int d = 0; d < NDT; ++d)
; #pragma unroll
;         for (int r = 0; r < 16; ++r) o[d][r] = 0.f;
; #pragma unroll
;     for (int ks = 0; ks < NKS; ++ks) asm volatile("" : "+v"(qf[ks]));
;     float mhat = 0.f, l = 0.f; f32x16 negm;
; #pragma unroll
;     for (int r = 0; r < 16; ++r) negm[r] = 0.f;
;     constexpr int TPB = (DV == 64) ? 2 : 1, NG = SEQL / 64 / TPB;
;     u32x4 kreg[TPB], k2reg[TPB], vreg[TPB][NVL];
;     const bf16_t* kptr = Kg + (size_t)(tid >> 3) * ldk + (tid & 7) * 8;
;     const bf16_t* k2ptr = (DQK == 96) ? K2g + (size_t)(tid >> 2) * ldk2 + (tid & 3) * 8 : nullptr;
;     ...
;     u32x4 pw[4];
; #pragma unroll
;     for (int j = 0; j < TPB; ++j) { ATT_LOAD(j, j); ATT_STORE(j, j); }
; #pragma unroll
;     for (int j = 0; j < TPB; ++j) ATT_LOAD(TPB + j, j);
;     const float qp = (float)(qpos0 + r32);
	v_lshlrev_b32_e32 v18, 16, v2
	v_and_b32_e32 v19, 0xffff0000, v2
	v_lshlrev_b32_e32 v2, 16, v3
	v_and_b32_e32 v3, 0xffff0000, v3
	v_pk_mul_f32 v[2:3], v[2:3], s[6:7] op_sel_hi:[1,0]
	v_pk_mul_f32 v[18:19], v[18:19], s[6:7] op_sel_hi:[1,0]
	v_cvt_pk_bf16_f32 v115, v2, v3
	v_lshlrev_b32_e32 v2, 16, v4
	v_and_b32_e32 v3, 0xffff0000, v4
	v_pk_mul_f32 v[2:3], v[2:3], s[6:7] op_sel_hi:[1,0]
	v_cvt_pk_bf16_f32 v114, v18, v19
	v_cvt_pk_bf16_f32 v116, v2, v3
	v_lshlrev_b32_e32 v2, 16, v5
	v_and_b32_e32 v3, 0xffff0000, v5
	v_pk_mul_f32 v[2:3], v[2:3], s[6:7] op_sel_hi:[1,0]
	s_nop 0
	v_cvt_pk_bf16_f32 v117, v2, v3
	s_waitcnt vmcnt(2)
	v_lshlrev_b32_e32 v2, 16, v6
	v_and_b32_e32 v3, 0xffff0000, v6
	v_pk_mul_f32 v[2:3], v[2:3], s[6:7] op_sel_hi:[1,0]
	s_nop 0
	v_cvt_pk_bf16_f32 v118, v2, v3
	v_lshlrev_b32_e32 v2, 16, v7
	v_and_b32_e32 v3, 0xffff0000, v7
	v_pk_mul_f32 v[2:3], v[2:3], s[6:7] op_sel_hi:[1,0]
	s_nop 0
	v_cvt_pk_bf16_f32 v119, v2, v3
	v_lshlrev_b32_e32 v2, 16, v8
	v_and_b32_e32 v3, 0xffff0000, v8
	v_pk_mul_f32 v[2:3], v[2:3], s[6:7] op_sel_hi:[1,0]
	v_lshlrev_b32_e32 v8, 3, v22
	v_cvt_pk_bf16_f32 v120, v2, v3
	v_lshlrev_b32_e32 v2, 16, v9
	v_and_b32_e32 v3, 0xffff0000, v9
	v_pk_mul_f32 v[2:3], v[2:3], s[6:7] op_sel_hi:[1,0]
	v_and_b32_e32 v27, 24, v8
	v_cvt_pk_bf16_f32 v121, v2, v3
	s_waitcnt vmcnt(1)
	v_lshlrev_b32_e32 v2, 16, v10
	v_and_b32_e32 v3, 0xffff0000, v10
	v_pk_mul_f32 v[2:3], v[2:3], s[6:7] op_sel_hi:[1,0]
	v_add_u32_e32 v10, 0x200, v22
	v_cvt_pk_bf16_f32 v122, v2, v3
	v_lshlrev_b32_e32 v2, 16, v11
	v_and_b32_e32 v3, 0xffff0000, v11
	v_pk_mul_f32 v[2:3], v[2:3], s[6:7] op_sel_hi:[1,0]
	v_lshlrev_b32_e32 v8, 1, v27
	v_cvt_pk_bf16_f32 v123, v2, v3
	v_lshlrev_b32_e32 v2, 16, v12
	v_and_b32_e32 v3, 0xffff0000, v12
	v_pk_mul_f32 v[2:3], v[2:3], s[6:7] op_sel_hi:[1,0]
	v_mov_b32_e32 v9, v151
	v_cvt_pk_bf16_f32 v124, v2, v3
	v_lshlrev_b32_e32 v2, 16, v13
	v_and_b32_e32 v3, 0xffff0000, v13
	v_pk_mul_f32 v[2:3], v[2:3], s[6:7] op_sel_hi:[1,0]
	v_ashrrev_i32_e32 v10, 3, v10
	v_cvt_pk_bf16_f32 v125, v2, v3
	s_waitcnt vmcnt(0)
	v_lshlrev_b32_e32 v2, 16, v14
	v_and_b32_e32 v3, 0xffff0000, v14
	v_pk_mul_f32 v[2:3], v[2:3], s[6:7] op_sel_hi:[1,0]
	v_and_b32_e32 v14, 0x70, v26
	v_cvt_pk_bf16_f32 v126, v2, v3
	v_lshlrev_b32_e32 v2, 16, v15
	v_and_b32_e32 v3, 0xffff0000, v15
	v_pk_mul_f32 v[2:3], v[2:3], s[6:7] op_sel_hi:[1,0]
	v_mov_b32_e32 v15, v151
	v_cvt_pk_bf16_f32 v127, v2, v3
	v_lshlrev_b32_e32 v2, 16, v16
	v_and_b32_e32 v3, 0xffff0000, v16
	v_pk_mul_f32 v[2:3], v[2:3], s[6:7] op_sel_hi:[1,0]
	v_and_b32_e32 v10, 0xffffffe0, v10
	v_cvt_pk_bf16_f32 v128, v2, v3
	v_lshlrev_b32_e32 v2, 16, v17
	v_and_b32_e32 v3, 0xffff0000, v17
	v_pk_mul_f32 v[2:3], v[2:3], s[6:7] op_sel_hi:[1,0]
	v_ashrrev_i32_e32 v11, 31, v10
	v_cvt_pk_bf16_f32 v129, v2, v3
	v_mov_b64_e32 v[2:3], s[4:5]
	v_mad_i64_i32 v[2:3], s[6:7], v25, s8, v[2:3]
	v_lshl_add_u64 v[144:145], v[2:3], 0, v[14:15]
	v_bfe_u32 v15, v22, 2, 6
	v_mul_u32_u24_e32 v2, 0xca0, v15
	v_lshlrev_b32_e32 v2, 1, v2
	v_mov_b32_e32 v3, v151
	v_lshl_add_u64 v[6:7], s[4:5], 0, v[2:3]
	global_load_dwordx4 v[2:5], v[144:145], off offset:1152
	v_lshl_add_u64 v[16:17], v[6:7], 0, v[8:9]
	v_and_b32_e32 v6, 0xffffffe0, v25
	s_movk_i32 s6, 0x90
	v_ashrrev_i32_e32 v7, 31, v6
	v_mul_lo_u32 v25, v25, s6
	v_lshlrev_b64 v[18:19], 1, v[6:7]
	v_lshlrev_b64 v[20:21], 1, v[10:11]
	v_add_u32_e32 v25, 0, v25
	v_lshl_add_u64 v[6:7], v[16:17], 0, v[18:19]
	v_lshl_add_u64 v[10:11], v[16:17], 0, v[20:21]
	v_add_u32_e32 v174, v25, v14
	s_mov_b64 s[4:5], 0x65800
	global_load_dwordx4 v[6:9], v[6:7], off offset:2048
	v_add3_u32 v14, 0, v29, v30
	global_load_dwordx4 v[10:13], v[10:11], off offset:2048
	v_and_b32_e32 v25, 0xfffff000, v26
	v_add_u32_e32 v175, v14, v25
	s_mov_b32 s7, 0
	s_waitcnt vmcnt(2)
	ds_write_b128 v174, v[2:5]
	v_lshl_add_u64 v[2:3], v[16:17], 0, s[4:5]
	v_lshl_add_u64 v[4:5], v[2:3], 0, v[18:19]
	s_mov_b32 s4, 0x65000
	global_load_dwordx4 v[130:133], v[4:5], off
	v_lshl_add_u64 v[2:3], v[2:3], 0, v[20:21]
	v_add_co_u32_e32 v4, vcc, s4, v144
	s_add_u32 s4, s9, s49
	s_nop 0
	v_addc_co_u32_e32 v5, vcc, 0, v145, vcc
	global_load_dwordx4 v[134:137], v[2:3], off
	global_load_dwordx4 v[138:141], v[4:5], off offset:1152
	v_or_b32_e32 v2, s3, v23
	v_cvt_f32_i32_e32 v176, v2
	v_and_or_b32 v2, v28, 3, v177
	v_lshlrev_b32_e32 v3, 1, v22
	v_lshl_add_u32 v2, v2, 6, 0
	v_and_b32_e32 v3, 32, v3
	s_addc_u32 s5, 0, s48
	v_add3_u32 v178, v2, v3, v27
	v_mov_b64_e32 v[2:3], s[4:5]
	v_and_b32_e32 v4, 3, v22
	v_mad_u64_u32 v[2:3], s[4:5], v15, s8, v[2:3]
	v_lshlrev_b32_e32 v4, 4, v4
	v_mov_b32_e32 v5, v151
	v_lshl_add_u64 v[2:3], v[2:3], 0, v[4:5]
	s_waitcnt vmcnt(4)
; template <int DQK, int DV, bool BIAS> ...
;     ...
; #pragma unroll
;     for (int d = 0; d < NDT; ++d)
; #pragma unroll
;         for (int r = 0; r < 16; ++r) o[d][r] = 0.f;
; #pragma unroll
;     for (int ks = 0; ks < NKS; ++ks) asm volatile("" : "+v"(qf[ks]));
;     float mhat = 0.f, l = 0.f; f32x16 negm;
; #pragma unroll
;     for (int r = 0; r < 16; ++r) negm[r] = 0.f;
;     constexpr int TPB = (DV == 64) ? 2 : 1, NG = SEQL / 64 / TPB;
;     u32x4 kreg[TPB], k2reg[TPB], vreg[TPB][NVL];
;     const bf16_t* kptr = Kg + (size_t)(tid >> 3) * ldk + (tid & 7) * 8;
;     const bf16_t* k2ptr = (DQK == 96) ? K2g + (size_t)(tid >> 2) * ldk2 + (tid & 3) * 8 : nullptr;
;     ...
;     u32x4 pw[4];
; #pragma unroll
;     for (int j = 0; j < TPB; ++j) { ATT_LOAD(j, j); ATT_STORE(j, j); }
; #pragma unroll
;     for (int j = 0; j < TPB; ++j) ATT_LOAD(TPB + j, j);
;     const float qp = (float)(qpos0 + r32);
	ds_write_b128 v175, v[6:9] offset:18432
	s_waitcnt vmcnt(3)
	ds_write_b128 v175, v[10:13] offset:26624
	v_mad_u32_u24 v6, v23, s6, 0
	v_lshl_add_u64 v[4:5], v[2:3], 0, v[20:21]
	v_lshl_add_u64 v[2:3], v[2:3], 0, v[18:19]
	v_lshl_add_u64 v[146:147], s[16:17], 0, v[4:5]
	v_lshl_add_u64 v[148:149], s[16:17], 0, v[2:3]
	s_mov_b32 s8, -2.0
	v_add_u32_e32 v179, v6, v150
	v_mov_b64_e32 v[18:19], v[50:51]
	v_mov_b64_e32 v[2:3], v[50:51]
	s_mov_b64 s[4:5], 0
	s_mov_b32 s6, 0xc2000000
	s_mov_b32 s9, 0xc0400000
	v_mov_b64_e32 v[20:21], v[52:53]
	v_mov_b64_e32 v[22:23], v[54:55]
	v_mov_b64_e32 v[24:25], v[56:57]
	v_mov_b64_e32 v[26:27], v[58:59]
	v_mov_b64_e32 v[28:29], v[60:61]
	v_mov_b64_e32 v[30:31], v[62:63]
	v_mov_b64_e32 v[32:33], v[64:65]
	v_mov_b64_e32 v[4:5], v[52:53]
	v_mov_b64_e32 v[6:7], v[54:55]
	v_mov_b64_e32 v[8:9], v[56:57]
	v_mov_b64_e32 v[10:11], v[58:59]
	v_mov_b64_e32 v[12:13], v[60:61]
	v_mov_b64_e32 v[14:15], v[62:63]
	v_mov_b64_e32 v[16:17], v[64:65]
	v_mbcnt_lo_u32_b32 v239, -1, 0
	v_mbcnt_hi_u32_b32 v239, -1, v239
	v_and_b32_e32 v238, 31, v239
	v_lshrrev_b32_e32 v237, 3, v238
	v_and_b32_e32 v236, 3, v238
	v_lshl_add_u32 v237, v237, 2, v236
	v_bfe_u32 v236, v238, 2, 1
	v_lshlrev_b32_e32 v236, 2, v236
	v_mov_b32_e32 v233, 0
	v_mov_b32_e32 v234, 0
	v_cmp_eq_u32_e64 s[98:99], 0, v237
	v_cndmask_b32_e64 v233, v233, 32, s[98:99]
	v_cndmask_b32_e64 v234, v234, 34, s[98:99]
	v_cmp_eq_u32_e64 s[98:99], 1, v237
	v_cndmask_b32_e64 v233, v233, 33, s[98:99]
	v_cndmask_b32_e64 v234, v234, 35, s[98:99]
	v_cmp_eq_u32_e64 s[98:99], 2, v237
	v_cndmask_b32_e64 v233, v233, 48, s[98:99]
	v_cndmask_b32_e64 v234, v234, 42, s[98:99]
	v_cmp_eq_u32_e64 s[98:99], 3, v237
	v_cndmask_b32_e64 v233, v233, 49, s[98:99]
	v_cndmask_b32_e64 v234, v234, 43, s[98:99]
	v_cmp_eq_u32_e64 s[98:99], 4, v237
	v_cndmask_b32_e64 v233, v233, 40, s[98:99]
	v_cndmask_b32_e64 v234, v234, 0, s[98:99]
	v_cmp_eq_u32_e64 s[98:99], 5, v237
	v_cndmask_b32_e64 v233, v233, 41, s[98:99]
	v_cndmask_b32_e64 v234, v234, 1, s[98:99]
	v_cmp_eq_u32_e64 s[98:99], 6, v237
	v_cndmask_b32_e64 v233, v233, 50, s[98:99]
	v_cndmask_b32_e64 v234, v234, 16, s[98:99]
	v_cmp_eq_u32_e64 s[98:99], 7, v237
	v_cndmask_b32_e64 v233, v233, 51, s[98:99]
	v_cndmask_b32_e64 v234, v234, 17, s[98:99]
	v_cmp_eq_u32_e64 s[98:99], 8, v237
	v_cndmask_b32_e64 v233, v233, 56, s[98:99]
	v_cndmask_b32_e64 v234, v234, 2, s[98:99]
	v_cmp_eq_u32_e64 s[98:99], 9, v237
	v_cndmask_b32_e64 v233, v233, 57, s[98:99]
	v_cndmask_b32_e64 v234, v234, 3, s[98:99]
	v_cmp_eq_u32_e64 s[98:99], 10, v237
	v_cndmask_b32_e64 v233, v233, 58, s[98:99]
	v_cndmask_b32_e64 v234, v234, 18, s[98:99]
	v_cmp_eq_u32_e64 s[98:99], 11, v237
	v_cndmask_b32_e64 v233, v233, 59, s[98:99]
	v_cndmask_b32_e64 v234, v234, 19, s[98:99]
	v_cmp_eq_u32_e64 s[98:99], 12, v237
	v_cndmask_b32_e64 v233, v233, 24, s[98:99]
	v_cndmask_b32_e64 v234, v234, 8, s[98:99]
	v_cmp_eq_u32_e64 s[98:99], 13, v237
	v_cndmask_b32_e64 v233, v233, 25, s[98:99]
	v_cndmask_b32_e64 v234, v234, 9, s[98:99]
	v_cmp_eq_u32_e64 s[98:99], 14, v237
	v_cndmask_b32_e64 v233, v233, 26, s[98:99]
	v_cndmask_b32_e64 v234, v234, 10, s[98:99]
	v_cmp_eq_u32_e64 s[98:99], 15, v237
	v_cndmask_b32_e64 v233, v233, 27, s[98:99]
	v_cndmask_b32_e64 v234, v234, 11, s[98:99]
	v_add_u32_e32 v233, v233, v236
	v_add_u32_e32 v234, v234, v236
	v_mul_u32_u24_e32 v235, 0x90, v238
	v_mul_u32_u24_e32 v240, 0x90, v233
	v_mul_u32_u24_e32 v241, 0x90, v234
	v_sub_u32_e32 v240, v240, v235
	v_sub_u32_e32 v241, v241, v235
	v_add_u32_e32 v240, v240, v179
	v_add_u32_e32 v241, v241, v179
	v_cvt_f32_u32_e32 v233, v233
	v_cvt_f32_u32_e32 v234, v234
	v_mul_f32_e32 v233, v142, v233
	v_mul_f32_e32 v234, v142, v234
	v_cmp_gt_u32_e64 s[98:99], 32, v239
	v_cndmask_b32_e64 v242, v233, 1.0, s[98:99]
	v_cndmask_b32_e64 v243, v234, 1.0, s[98:99]
	v_xor_b32_e32 v233, 0x80000000, v233
	v_xor_b32_e32 v234, 0x80000000, v234
	v_cndmask_b32_e64 v244, v233, 1.0, s[98:99]
	v_cndmask_b32_e64 v245, v234, 1.0, s[98:99]
	v_xor_b32_e32 v231, 0x80000000, v142
	v_cndmask_b32_e64 v231, 0, v231, s[98:99]
	v_cndmask_b32_e64 v232, 1.0, 0, s[98:99]
	s_branch .LBB0_588

; #define LAS __attribute__((address_space(3)))
; template <int DQK, int DV, bool BIAS> ...
;     ...
;       for (int sub = 0; sub < TPB; ++sub) {
;         const int t = g * TPB + sub, buf = pair * TPB + sub, vcur = buf;
;         f32x16 p0, p1;
;         const LAS unsigned char* kb = lds + buf * KBUF + r32 * KP + hi * 16;
; #pragma unroll
;         for (int ks = 0; ks < NKS; ++ks) {
;             const bf16x8 k0 = *(const LAS bf16x8*)(kb + ks * 32), k1 = *(const LAS bf16x8*)(kb + 32 * KP + ks * 32);
;             if (ks == 0) { p0 = __builtin_amdgcn_mfma_f32_32x32x16_bf16(k0, qf[0], negm, 0, 0, 0); p1 = __builtin_amdgcn_mfma_f32_32x32x16_bf16(k1, qf[0], negm, 0, 0, 0); }
;             else { p0 = __builtin_amdgcn_mfma_f32_32x32x16_bf16(k0, qf[ks], p0, 0, 0, 0); p1 = __builtin_amdgcn_mfma_f32_32x32x16_bf16(k1, qf[ks], p1, 0, 0, 0); }
;         }
;         if (BIAS) {
;             asm volatile("s_nop 15\n\ts_nop 7" : "+v"(p0), "+v"(p1));
;             const float d0 = qp - (float)(t * 64 + 4 * hi);
; #pragma unroll
;             for (int r = 0; r < 16; ++r) { const float dk = d0 - (float)((r & 3) + 8 * (r >> 2)); p0[r] = p0[r] - sl2 * fabsf(dk); p1[r] = p1[r] - sl2 * fabsf(dk - 32.f); }
;         } else {
;             asm volatile("s_nop 15\n\ts_nop 7" : "+v"(p0), "+v"(p1));
;         }
.LBB0_590:
	ds_read_b128 v[82:85], v240
	ds_read_b128 v[86:89], v240 offset:32
	ds_read_b128 v[90:93], v241
	ds_read_b128 v[94:97], v241 offset:32
	v_cvt_f32_u32_e32 v150, v177
	s_waitcnt lgkmcnt(3)
	v_mfma_f32_32x32x16_bf16 v[98:113], v[82:85], v[114:117], v[66:81]
	v_sub_f32_e32 v182, v176, v150
	s_waitcnt lgkmcnt(1)
	v_mfma_f32_32x32x16_bf16 v[152:167], v[90:93], v[114:117], v[66:81]
	v_mfma_f32_32x32x16_bf16 v[98:113], v[86:89], v[118:121], v[98:113]
	ds_read_b128 v[82:85], v240 offset:64
	ds_read_b128 v[86:89], v240 offset:96
	s_waitcnt lgkmcnt(2)
	v_mfma_f32_32x32x16_bf16 v[152:167], v[94:97], v[118:121], v[152:167]
	s_waitcnt lgkmcnt(1)
	v_mfma_f32_32x32x16_bf16 v[98:113], v[82:85], v[122:125], v[98:113]
	ds_read_b128 v[90:93], v241 offset:64
	ds_read_b128 v[94:97], v241 offset:96
	s_waitcnt lgkmcnt(1)
	v_mfma_f32_32x32x16_bf16 v[152:167], v[90:93], v[122:125], v[152:167]
	v_mfma_f32_32x32x16_bf16 v[98:113], v[86:89], v[126:129], v[98:113]
	s_waitcnt lgkmcnt(0)
	v_mfma_f32_32x32x16_bf16 v[152:167], v[94:97], v[126:129], v[152:167]
	v_readfirstlane_b32 s98, v182
	s_nop 8
	s_cmp_lt_i32 s98, 0
	s_cbranch_scc1 .Lfb2_r
	s_cmp_lt_u32 s98, 0x42800000
	s_cbranch_scc1 .Lfb2_d
	v_fma_f32 v230, v231, v182, v232
	s_nop 1
	v_mfma_f32_32x32x2_f32 v[98:113], v242, v230, v[98:113]
	v_mfma_f32_32x32x2_f32 v[152:167], v243, v230, v[152:167]
	s_branch .Lfb2_j
.Lfb2_r:
	v_fma_f32 v230, -v231, v182, v232
	s_nop 1
	v_mfma_f32_32x32x2_f32 v[98:113], v244, v230, v[98:113]
	v_mfma_f32_32x32x2_f32 v[152:167], v245, v230, v[152:167]

; __device__ __forceinline__ float max3f(float a, float b, float c) { float r; asm("v_max3_f32 %0, %1, %2, %3" : "=v"(r) : "v"(a), "v"(b), "v"(c)); return r; }
; template <int DQK, int DV, bool BIAS> ...
;     ...
;             for (int r = 0; r < 16; ++r) { const float dk = d0 - (float)((r & 3) + 8 * (r >> 2)); p0[r] = p0[r] - sl2 * fabsf(dk); p1[r] = p1[r] - sl2 * fabsf(dk - 32.f); }
;         } else {
;             asm volatile("s_nop 15\n\ts_nop 7" : "+v"(p0), "+v"(p1));
;         }
;         float mxa = max3f(p0[0], p0[1], p1[0]), mxb = max3f(p0[2], p0[3], p1[1]); mxa = max3f(mxa, p1[2], p1[3]);
; #pragma unroll
;         for (int r = 4; r < 16; r += 4) { mxa = max3f(mxa, p0[r], p0[r + 1]); mxb = max3f(mxb, p0[r + 2], p0[r + 3]); mxa = max3f(mxa, p1[r], p1[r + 1]); mxb = max3f(mxb, p1[r + 2], p1[r + 3]); }
;         float mx = fmaxf(mxa, mxb);
;         if (__any(mx > 8.f)) {
;             mx = fmaxf(mx, __shfl_xor(mx, 32));
;             const float dl = fmaxf(mx, 0.f); mhat += dl;
;             const float f = __builtin_amdgcn_exp2f(-dl);
; #pragma unroll
;             for (int r = 0; r < 16; ++r) { p0[r] -= dl; p1[r] -= dl; negm[r] = -mhat; }
;             l *= f;
; #pragma unroll
;             for (int d = 0; d < NDT; ++d)
; #pragma unroll
;                 for (int r = 0; r < 16; ++r) o[d][r] *= f;
;         }
.Lfb2_d:
	s_nop 7
	v_add_f32_e32 v239, 0xc2000000, v182
	v_fma_f32 v98, -v142, |v239|, v98
	v_add_f32_e32 v239, 0xc2040000, v182
	v_fma_f32 v99, -v142, |v239|, v99
	v_add_f32_e32 v239, 0xc2400000, v182
	v_fma_f32 v100, -v142, |v239|, v100
	v_add_f32_e32 v239, 0xc2440000, v182
	v_fma_f32 v101, -v142, |v239|, v101
	v_add_f32_e32 v239, 0xc2200000, v182
	v_fma_f32 v102, -v142, |v239|, v102
	v_add_f32_e32 v239, 0xc2240000, v182
	v_fma_f32 v103, -v142, |v239|, v103
	v_add_f32_e32 v239, 0xc2480000, v182
	v_fma_f32 v104, -v142, |v239|, v104
	v_add_f32_e32 v239, 0xc24c0000, v182
	v_fma_f32 v105, -v142, |v239|, v105
	v_add_f32_e32 v239, 0xc2600000, v182
	v_fma_f32 v106, -v142, |v239|, v106
	v_add_f32_e32 v239, 0xc2640000, v182
	v_fma_f32 v107, -v142, |v239|, v107
	v_add_f32_e32 v239, 0xc2680000, v182
	v_fma_f32 v108, -v142, |v239|, v108
	v_add_f32_e32 v239, 0xc26c0000, v182
	v_fma_f32 v109, -v142, |v239|, v109
	v_add_f32_e32 v239, 0xc1c00000, v182
	v_fma_f32 v110, -v142, |v239|, v110
	v_add_f32_e32 v239, 0xc1c80000, v182
	v_fma_f32 v111, -v142, |v239|, v111
	v_add_f32_e32 v239, 0xc1d00000, v182
	v_fma_f32 v112, -v142, |v239|, v112
	v_add_f32_e32 v239, 0xc1d80000, v182
	v_fma_f32 v113, -v142, |v239|, v113
	v_add_f32_e32 v239, 0xc2080000, v182
	v_fma_f32 v152, -v142, |v239|, v152
	v_add_f32_e32 v239, 0xc20c0000, v182
	v_fma_f32 v153, -v142, |v239|, v153
	v_add_f32_e32 v239, 0xc2280000, v182
	v_fma_f32 v154, -v142, |v239|, v154
	v_add_f32_e32 v239, 0xc22c0000, v182
	v_fma_f32 v155, -v142, |v239|, v155
	v_fma_f32 v156, -v142, |v182|, v156
	v_add_f32_e32 v239, 0xbf800000, v182
	v_fma_f32 v157, -v142, |v239|, v157
	v_add_f32_e32 v239, 0xc1800000, v182
	v_fma_f32 v158, -v142, |v239|, v158
	v_add_f32_e32 v239, 0xc1880000, v182
	v_fma_f32 v159, -v142, |v239|, v159
	v_add_f32_e32 v239, 0xc0000000, v182
	v_fma_f32 v160, -v142, |v239|, v160
	v_add_f32_e32 v239, 0xc0400000, v182
	v_fma_f32 v161, -v142, |v239|, v161
	v_add_f32_e32 v239, 0xc1900000, v182
	v_fma_f32 v162, -v142, |v239|, v162
	v_add_f32_e32 v239, 0xc1980000, v182
	v_fma_f32 v163, -v142, |v239|, v163
	v_add_f32_e32 v239, 0xc1000000, v182
	v_fma_f32 v164, -v142, |v239|, v164
	v_add_f32_e32 v239, 0xc1100000, v182
	v_fma_f32 v165, -v142, |v239|, v165
	v_add_f32_e32 v239, 0xc1200000, v182
	v_fma_f32 v166, -v142, |v239|, v166
	v_add_f32_e32 v239, 0xc1300000, v182
	v_fma_f32 v167, -v142, |v239|, v167
.Lfb2_m:
	v_max3_f32 v82, v156, v157, v98
	v_max3_f32 v83, v160, v161, v99
	v_max3_f32 v82, v82, v152, v153
	v_max3_f32 v83, v83, v166, v167
	v_max3_f32 v82, v82, v164, v165
	v_max3_f32 v83, v83, v154, v155
	v_max3_f32 v82, v82, v102, v103
	v_max3_f32 v83, v83, v162, v163
	v_max3_f32 v82, v82, v158, v159
	v_max3_f32 v83, v83, v104, v105
	v_max3_f32 v82, v82, v100, v101
	v_max3_f32 v83, v83, v112, v113
	v_max3_f32 v82, v82, v110, v111
	v_max3_f32 v83, v83, v108, v109
	v_max3_f32 v82, v82, v106, v107
	v_max_f32_e32 v82, v82, v83
	v_cmp_gt_f32_e32 vcc, 0xc3400000, v82
	s_cmp_eq_u64 vcc, exec
	s_cbranch_scc1 .Lsk1_p4a2
	v_cmp_lt_f32_e32 vcc, s44, v82
	s_cbranch_vccz .LBB0_592
	ds_bpermute_b32 v66, v168, v82
	s_waitcnt lgkmcnt(0)
	v_max3_f32 v67, v82, v66, 0
	v_exp_f32_e64 v66, -v67
	v_add_f32_e32 v180, v180, v67
	v_xor_b32_e32 v82, 0x80000000, v180
	v_sub_f32_e32 v98, v98, v67
	v_sub_f32_e32 v99, v99, v67
	v_sub_f32_e32 v152, v152, v67
	v_sub_f32_e32 v153, v153, v67
	v_sub_f32_e32 v102, v102, v67
	v_sub_f32_e32 v103, v103, v67
	v_sub_f32_e32 v154, v154, v67
	v_sub_f32_e32 v155, v155, v67
	v_sub_f32_e32 v100, v100, v67
	v_sub_f32_e32 v101, v101, v67
	v_sub_f32_e32 v104, v104, v67
	v_sub_f32_e32 v105, v105, v67
	v_sub_f32_e32 v106, v106, v67
	v_sub_f32_e32 v107, v107, v67
	v_sub_f32_e32 v108, v108, v67
	v_sub_f32_e32 v109, v109, v67
	v_pk_mul_f32 v[16:17], v[16:17], v[66:67] op_sel_hi:[1,0]
	v_pk_mul_f32 v[14:15], v[14:15], v[66:67] op_sel_hi:[1,0]
	v_pk_mul_f32 v[12:13], v[12:13], v[66:67] op_sel_hi:[1,0]
	v_pk_mul_f32 v[10:11], v[10:11], v[66:67] op_sel_hi:[1,0]
	v_pk_mul_f32 v[8:9], v[8:9], v[66:67] op_sel_hi:[1,0]
	v_pk_mul_f32 v[6:7], v[6:7], v[66:67] op_sel_hi:[1,0]
	v_pk_mul_f32 v[4:5], v[4:5], v[66:67] op_sel_hi:[1,0]
	v_pk_mul_f32 v[2:3], v[2:3], v[66:67] op_sel_hi:[1,0]
	v_pk_mul_f32 v[32:33], v[32:33], v[66:67] op_sel_hi:[1,0]
	v_pk_mul_f32 v[30:31], v[30:31], v[66:67] op_sel_hi:[1,0]
	v_pk_mul_f32 v[28:29], v[28:29], v[66:67] op_sel_hi:[1,0]
	v_pk_mul_f32 v[26:27], v[26:27], v[66:67] op_sel_hi:[1,0]
	v_pk_mul_f32 v[24:25], v[24:25], v[66:67] op_sel_hi:[1,0]
	v_pk_mul_f32 v[22:23], v[22:23], v[66:67] op_sel_hi:[1,0]
	v_pk_mul_f32 v[20:21], v[20:21], v[66:67] op_sel_hi:[1,0]
	v_pk_mul_f32 v[18:19], v[18:19], v[66:67] op_sel_hi:[1,0]
	v_pk_mul_f32 v[48:49], v[48:49], v[66:67] op_sel_hi:[1,0]
	v_pk_mul_f32 v[46:47], v[46:47], v[66:67] op_sel_hi:[1,0]
	v_pk_mul_f32 v[44:45], v[44:45], v[66:67] op_sel_hi:[1,0]
	v_pk_mul_f32 v[42:43], v[42:43], v[66:67] op_sel_hi:[1,0]
	v_pk_mul_f32 v[40:41], v[40:41], v[66:67] op_sel_hi:[1,0]
	v_pk_mul_f32 v[38:39], v[38:39], v[66:67] op_sel_hi:[1,0]
	v_pk_mul_f32 v[36:37], v[36:37], v[66:67] op_sel_hi:[1,0]
	v_pk_mul_f32 v[34:35], v[34:35], v[66:67] op_sel_hi:[1,0]
	v_pk_mul_f32 v[64:65], v[64:65], v[66:67] op_sel_hi:[1,0]
	v_pk_mul_f32 v[62:63], v[62:63], v[66:67] op_sel_hi:[1,0]
	v_pk_mul_f32 v[60:61], v[60:61], v[66:67] op_sel_hi:[1,0]
	v_pk_mul_f32 v[58:59], v[58:59], v[66:67] op_sel_hi:[1,0]
	v_pk_mul_f32 v[56:57], v[56:57], v[66:67] op_sel_hi:[1,0]
	v_pk_mul_f32 v[54:55], v[54:55], v[66:67] op_sel_hi:[1,0]
	v_pk_mul_f32 v[52:53], v[52:53], v[66:67] op_sel_hi:[1,0]
	v_pk_mul_f32 v[50:51], v[50:51], v[66:67] op_sel_hi:[1,0]
	v_sub_f32_e32 v156, v156, v67
	v_sub_f32_e32 v157, v157, v67
	v_sub_f32_e32 v160, v160, v67
	v_sub_f32_e32 v161, v161, v67
	v_sub_f32_e32 v164, v164, v67
	v_sub_f32_e32 v165, v165, v67
	v_sub_f32_e32 v166, v166, v67
	v_sub_f32_e32 v167, v167, v67
	v_sub_f32_e32 v158, v158, v67
	v_sub_f32_e32 v159, v159, v67
	v_sub_f32_e32 v162, v162, v67
	v_sub_f32_e32 v163, v163, v67
	v_sub_f32_e32 v110, v110, v67
	v_sub_f32_e32 v111, v111, v67
	v_sub_f32_e32 v112, v112, v67
	v_sub_f32_e32 v113, v113, v67
	v_mul_f32_e32 v151, v151, v66
	v_mov_b32_e32 v66, v82
	v_mov_b32_e32 v67, v82
	v_mov_b32_e32 v68, v82
	v_mov_b32_e32 v69, v82
	v_mov_b32_e32 v70, v82
	v_mov_b32_e32 v71, v82
	v_mov_b32_e32 v72, v82
	v_mov_b32_e32 v73, v82
	v_mov_b32_e32 v74, v82
	v_mov_b32_e32 v75, v82
	v_mov_b32_e32 v76, v82
	v_mov_b32_e32 v77, v82
	v_mov_b32_e32 v78, v82
	v_mov_b32_e32 v79, v82
	v_mov_b32_e32 v80, v82
	v_mov_b32_e32 v81, v82
	s_branch .LBB0_593

; template <int DQK, int DV, bool BIAS> ...
;     ...
;     int tid_ = threadIdx.x; asm volatile("" : "+v"(tid_));
;     const int tid = tid_, lane = tid & 63, r32 = lane & 31, hi = lane >> 5;
;     const bool isY = false;
;     bf16x8 qf[NKS];
; #pragma unroll
;     for (int ks = 0; ks < NKS; ++ks) qf[ks] = ks < 4 ? *(const bf16x8*)(Qw + (size_t)r32 * ldq + ks * 16 + hi * 8) : *(const bf16x8*)(Q2w + (size_t)r32 * ldq2 + (ks - 4) * 16 + hi * 8);
; #pragma unroll
;     for (int ks = 0; ks < 4; ++ks) qf[ks] = scale_frag(qf[ks], cs);
;     if constexpr (DQK == 96) {
;         const float* rp = ropetab + ((size_t)(qpos0 + r32) * 16) * 2;
; #pragma unroll
;         for (int ks = 4; ks < 6; ++ks) {
;             const f32x4 c0 = *(const f32x4*)(rp + ((ks - 4) * 8 + hi * 4) * 2), c1 = *(const f32x4*)(rp + ((ks - 4) * 8 + hi * 4 + 2) * 2);
;             const u32x4 w = __builtin_bit_cast(u32x4, qf[ks]); u32x4 ow;
;             { const float a = bflo(w.x) * cs, b = bfhi(w.x) * cs; ow.x = cvtpk(a * c0[0] - b * c0[1], a * c0[1] + b * c0[0]); }
;             { const float a = bflo(w.y) * cs, b = bfhi(w.y) * cs; ow.y = cvtpk(a * c0[2] - b * c0[3], a * c0[3] + b * c0[2]); }
;             { const float a = bflo(w.z) * cs, b = bfhi(w.z) * cs; ow.z = cvtpk(a * c1[0] - b * c1[1], a * c1[1] + b * c1[0]); }
;             { const float a = bflo(w.w) * cs, b = bfhi(w.w) * cs; ow.w = cvtpk(a * c1[2] - b * c1[3], a * c1[3] + b * c1[2]); }
;             qf[ks] = __builtin_bit_cast(bf16x8, ow);
;         }
;     }
; #pragma unroll
;     for (int d = 0; d < NDT; ++d)
; #pragma unroll
;         for (int r = 0; r < 16; ++r) o[d][r] = 0.f;
; #pragma unroll
;     for (int ks = 0; ks < NKS; ++ks) asm volatile("" : "+v"(qf[ks]));
;     float mhat = 0.f, l = 0.f; f32x16 negm;
; __device__ __forceinline__ void attn_phase(PPtr P, int li, LAS unsigned char* lds, int vcu, int wave, int lane) {
;     ...
;         const int b = vcu >> 6, h = (vcu >> 4) & 3, qb = vcu & 15;
;         const size_t seq0 = (size_t)b * SEQL, qrow = seq0 + qb * 256 + wave * 32;
;         const float slope = __builtin_amdgcn_exp2f(-2.f * (float)(h + 1));
;         f32x16 o1[4], o2[4];
;         attn_pass<64, 128, true>(lds, proj + qrow * LDP + C_AQ + h * 128, LDP, nullptr, 0, proj + seq0 * LDP + C_AK + h * 128, LDP, nullptr, 0, proj + seq0 * LDP + C_AV + h * 128, LDP, qb * 256 + wave * 32, 0.125f * LOG2E, slope * LOG2E, nullptr, o1);
.LBB0_2001:
	s_cmp_lt_i32 s24, 15
	s_cselect_b64 s[4:5], -1, 0
	s_cmp_gt_i32 s25, 14
	s_cselect_b64 s[6:7], -1, 0
	s_and_b64 s[4:5], s[4:5], s[6:7]
	s_andn2_b64 vcc, exec, s[4:5]
	s_cbranch_vccnz .LBB0_2179
	s_mov_b64 s[20:21], s[0:1]
	v_mov_b32_e32 v169, v1
	s_load_dwordx2 s[16:17], s[20:21], 0x118
	s_ashr_i32 s4, s33, 6
	v_readfirstlane_b32 s3, v169
	s_ashr_i32 s50, s3, 6
	s_ashr_i32 s5, s4, 31
	s_lshl_b32 s3, s33, 8
	s_lshl_b64 s[6:7], s[4:5], 12
	s_and_b32 s27, s3, 0xf00
	s_lshl_b32 s46, s50, 5
	s_bfe_u32 s8, s33, 0x20004
	s_or_b32 s3, s6, s27
	s_ashr_i32 s47, s46, 31
	s_add_u32 s5, s3, s46
	s_addc_u32 s6, s7, s47
	s_not_b32 s3, s8
	s_mulk_i32 s6, 0x1940
	s_mul_hi_u32 s7, s5, 0x1940
	s_lshl_b32 s3, s3, 1
	s_add_i32 s7, s7, s6
	s_mulk_i32 s5, 0x1940
	s_waitcnt lgkmcnt(0)
	s_add_u32 s5, s16, s5
	v_mov_b32_e32 v32, v1
	s_addc_u32 s6, s17, s7
	s_lshl_b32 s9, s8, 8
	s_add_u32 s18, s5, s9
	v_and_b32_e32 v33, 31, v32
	v_mul_u32_u24_e32 v2, 0xca0, v33
	s_addc_u32 s19, s6, 0
	v_bfe_u32 v34, v32, 5, 1
	v_lshlrev_b32_e32 v150, 1, v2
	v_mov_b32_e32 v151, 0
	v_lshl_add_u64 v[2:3], s[18:19], 0, v[150:151]
	v_lshlrev_b32_e32 v150, 4, v34
	v_lshl_add_u64 v[18:19], v[2:3], 0, v[150:151]
	global_load_dwordx4 v[2:5], v[18:19], off
	global_load_dwordx4 v[6:9], v[18:19], off offset:32
	global_load_dwordx4 v[10:13], v[18:19], off offset:64
	global_load_dwordx4 v[14:17], v[18:19], off offset:96
	s_movk_i32 s7, 0x1940
	s_mov_b32 s6, 0x3e38aa3b
	s_mul_i32 s49, s4, 0x1940000
	s_mul_hi_i32 s48, s4, 0x1940000
	s_add_u32 s4, s16, s49
	s_addc_u32 s5, s17, s48
	s_add_u32 s4, s4, s9
	s_addc_u32 s5, s5, 0
	s_mov_b32 s8, 0x65000
	v_lshlrev_b32_e32 v173, 2, v34
	s_mov_b32 s22, 0xc1000000
	s_mov_b32 s34, 0xc1200000
	s_mov_b32 s36, 0xc1800000
	s_mov_b32 s38, 0xc1900000
	s_mov_b32 s40, 0xc1c00000
	s_mov_b32 s42, 0xc1d00000
	s_mov_b32 s51, 0
	s_mov_b32 s23, 0xc1100000
	s_mov_b32 s35, 0xc1300000
	s_mov_b32 s37, 0xc1880000
	s_mov_b32 s39, 0xc1980000
	s_mov_b32 s41, 0xc1c80000
	s_mov_b32 s43, 0xc1d80000
	s_mov_b32 s52, 0x41000000
	v_mov_b32_e32 v176, v151
	v_mov_b32_e32 v66, v151
	v_mov_b32_e32 v67, v151
	v_mov_b32_e32 v68, v151
	v_mov_b32_e32 v69, v151
	v_mov_b32_e32 v70, v151
	v_mov_b32_e32 v71, v151
	v_mov_b32_e32 v72, v151
	v_mov_b32_e32 v73, v151
	v_mov_b32_e32 v74, v151
	v_mov_b32_e32 v75, v151
	v_mov_b32_e32 v76, v151
	v_mov_b32_e32 v77, v151
	v_mov_b32_e32 v78, v151
	v_mov_b32_e32 v79, v151
	v_mov_b32_e32 v80, v151
	v_mov_b32_e32 v81, v151
	s_waitcnt vmcnt(0)
	v_lshlrev_b32_e32 v18, 16, v2
	v_and_b32_e32 v19, 0xffff0000, v2
	v_lshlrev_b32_e32 v2, 16, v3
	v_and_b32_e32 v3, 0xffff0000, v3
	v_lshlrev_b32_e32 v30, 16, v14
	v_pk_mul_f32 v[2:3], v[2:3], s[6:7] op_sel_hi:[1,0]
	v_and_b32_e32 v31, 0xffff0000, v14
	v_cvt_pk_bf16_f32 v115, v2, v3
	v_pk_mul_f32 v[2:3], v[30:31], s[6:7] op_sel_hi:[1,0]
	v_lshlrev_b32_e32 v22, 16, v6
	v_cvt_pk_bf16_f32 v126, v2, v3
	v_lshlrev_b32_e32 v2, 16, v15
	v_and_b32_e32 v3, 0xffff0000, v15
	v_pk_mul_f32 v[2:3], v[2:3], s[6:7] op_sel_hi:[1,0]
	v_and_b32_e32 v23, 0xffff0000, v6
	v_cvt_pk_bf16_f32 v127, v2, v3
	v_lshlrev_b32_e32 v2, 16, v16
	v_and_b32_e32 v3, 0xffff0000, v16
	v_pk_mul_f32 v[2:3], v[2:3], s[6:7] op_sel_hi:[1,0]
	v_lshlrev_b32_e32 v24, 16, v8
	v_cvt_pk_bf16_f32 v128, v2, v3
	v_lshlrev_b32_e32 v2, 16, v17
	v_and_b32_e32 v3, 0xffff0000, v17
	v_and_b32_e32 v25, 0xffff0000, v8
	v_pk_mul_f32 v[22:23], v[22:23], s[6:7] op_sel_hi:[1,0]
	v_pk_mul_f32 v[2:3], v[2:3], s[6:7] op_sel_hi:[1,0]
	v_lshlrev_b32_e32 v20, 16, v4
	v_and_b32_e32 v21, 0xffff0000, v4
	v_lshlrev_b32_e32 v4, 16, v5
	v_and_b32_e32 v5, 0xffff0000, v5
	v_pk_mul_f32 v[24:25], v[24:25], s[6:7] op_sel_hi:[1,0]
	v_cvt_pk_bf16_f32 v118, v22, v23
	v_cvt_pk_bf16_f32 v129, v2, v3
	v_ashrrev_i32_e32 v22, 3, v32
	v_mov_b64_e32 v[2:3], s[4:5]
	v_lshlrev_b32_e32 v23, 4, v32
	v_pk_mul_f32 v[4:5], v[4:5], s[6:7] op_sel_hi:[1,0]
	v_cvt_pk_bf16_f32 v120, v24, v25
	v_mad_i64_i32 v[2:3], s[10:11], v22, s7, v[2:3]
	v_and_b32_e32 v14, 0x70, v23
	v_mov_b32_e32 v15, v151
	v_bfe_u32 v24, v32, 2, 6
	v_cvt_pk_bf16_f32 v117, v4, v5
	v_lshl_add_u64 v[144:145], v[2:3], 0, v[14:15]
	v_mul_u32_u24_e32 v2, 0xca0, v24
	v_lshlrev_b32_e32 v4, 3, v32
	v_lshlrev_b32_e32 v2, 1, v2
	v_mov_b32_e32 v3, v151
	v_and_b32_e32 v25, 24, v4
	v_lshl_add_u64 v[2:3], s[4:5], 0, v[2:3]
	v_lshlrev_b32_e32 v4, 1, v25
	v_mov_b32_e32 v5, v151
	v_lshl_add_u64 v[16:17], v[2:3], 0, v[4:5]
	v_and_b32_e32 v2, 0xffffffe0, v22
	v_lshlrev_b32_e32 v6, 16, v7
	v_and_b32_e32 v7, 0xffff0000, v7
	v_lshlrev_b32_e32 v8, 16, v9
	v_and_b32_e32 v9, 0xffff0000, v9
	v_lshlrev_b32_e32 v26, 16, v10
	v_and_b32_e32 v27, 0xffff0000, v10
	v_lshlrev_b32_e32 v10, 16, v11
	v_and_b32_e32 v11, 0xffff0000, v11
	v_lshlrev_b32_e32 v28, 16, v12
	v_and_b32_e32 v29, 0xffff0000, v12
	v_lshlrev_b32_e32 v12, 16, v13
	v_and_b32_e32 v13, 0xffff0000, v13
	v_pk_mul_f32 v[18:19], v[18:19], s[6:7] op_sel_hi:[1,0]
	v_ashrrev_i32_e32 v3, 31, v2
	v_pk_mul_f32 v[20:21], v[20:21], s[6:7] op_sel_hi:[1,0]
	v_pk_mul_f32 v[6:7], v[6:7], s[6:7] op_sel_hi:[1,0]
	v_pk_mul_f32 v[8:9], v[8:9], s[6:7] op_sel_hi:[1,0]
	v_pk_mul_f32 v[26:27], v[26:27], s[6:7] op_sel_hi:[1,0]
	v_pk_mul_f32 v[10:11], v[10:11], s[6:7] op_sel_hi:[1,0]
	v_pk_mul_f32 v[28:29], v[28:29], s[6:7] op_sel_hi:[1,0]
	v_pk_mul_f32 v[12:13], v[12:13], s[6:7] op_sel_hi:[1,0]
	v_cvt_pk_bf16_f32 v114, v18, v19
	v_lshlrev_b64 v[18:19], 1, v[2:3]
	v_cvt_pk_bf16_f32 v116, v20, v21
	v_cvt_pk_bf16_f32 v119, v6, v7
	v_cvt_pk_bf16_f32 v121, v8, v9
	v_cvt_pk_bf16_f32 v122, v26, v27
	v_cvt_pk_bf16_f32 v123, v10, v11
	v_cvt_pk_bf16_f32 v124, v28, v29
	v_cvt_pk_bf16_f32 v125, v12, v13
	v_lshl_add_u64 v[10:11], v[16:17], 0, v[18:19]
	global_load_dwordx4 v[2:5], v[144:145], off offset:1024
	global_load_dwordx4 v[6:9], v[10:11], off offset:2048
	v_add_u32_e32 v10, 0x200, v32
	v_ashrrev_i32_e32 v10, 3, v10
	v_and_b32_e32 v10, 0xffffffe0, v10
	v_ashrrev_i32_e32 v11, 31, v10
	v_lshlrev_b64 v[20:21], 1, v[10:11]
	v_lshl_add_u64 v[10:11], v[16:17], 0, v[20:21]
	global_load_dwordx4 v[10:13], v[10:11], off offset:2048
	s_movk_i32 s6, 0x90
	v_mul_lo_u32 v15, v22, s6
	s_mov_b64 s[10:11], 0x65800
	v_and_b32_e32 v22, 0xfc0, v23
	v_and_b32_e32 v27, 48, v23
	v_add_u32_e32 v15, 0, v15
	v_and_b32_e32 v23, 0xfffff000, v23
	v_add3_u32 v22, 0, v22, v27
	v_add_u32_e32 v168, v15, v14
	v_lshl_add_u64 v[14:15], v[16:17], 0, s[10:11]
	v_add_u32_e32 v171, v22, v23
	v_lshl_add_u64 v[16:17], v[14:15], 0, v[18:19]
	v_add_co_u32_e32 v22, vcc, s8, v144
	v_lshl_add_u64 v[14:15], v[14:15], 0, v[20:21]
	s_nop 0
	v_addc_co_u32_e32 v23, vcc, 0, v145, vcc
	global_load_dwordx4 v[130:133], v[16:17], off
	global_load_dwordx4 v[134:137], v[14:15], off
	global_load_dwordx4 v[138:141], v[22:23], off offset:1024
	v_cvt_f32_i32_e32 v28, s3
	s_add_i32 s3, s46, s27
	v_lshrrev_b32_e32 v26, 2, v32
	s_waitcnt vmcnt(5)
; template <int DQK, int DV, bool BIAS> ...
;     ...
; #pragma unroll
;     for (int d = 0; d < NDT; ++d)
; #pragma unroll
;         for (int r = 0; r < 16; ++r) o[d][r] = 0.f;
; #pragma unroll
;     for (int ks = 0; ks < NKS; ++ks) asm volatile("" : "+v"(qf[ks]));
;     float mhat = 0.f, l = 0.f; f32x16 negm;
; #pragma unroll
;     for (int r = 0; r < 16; ++r) negm[r] = 0.f;
;     constexpr int TPB = (DV == 64) ? 2 : 1, NG = SEQL / 64 / TPB;
;     u32x4 kreg[TPB], k2reg[TPB], vreg[TPB][NVL];
;     const bf16_t* kptr = Kg + (size_t)(tid >> 3) * ldk + (tid & 7) * 8;
;     const bf16_t* k2ptr = (DQK == 96) ? K2g + (size_t)(tid >> 2) * ldk2 + (tid & 3) * 8 : nullptr;
;     ...
;     u32x4 pw[4];
; #pragma unroll
;     for (int j = 0; j < TPB; ++j) { ATT_LOAD(j, j); ATT_STORE(j, j); }
; #pragma unroll
;     for (int j = 0; j < TPB; ++j) ATT_LOAD(TPB + j, j);
;     const float qp = (float)(qpos0 + r32);
; __device__ __forceinline__ void attn_phase(PPtr P, int li, LAS unsigned char* lds, int vcu, int wave, int lane) {
;     ...
;         const float slope = __builtin_amdgcn_exp2f(-2.f * (float)(h + 1));
	ds_write_b128 v168, v[2:5]
	s_waitcnt vmcnt(4)
	ds_write_b128 v171, v[6:9] offset:18432
	s_waitcnt vmcnt(3)
	ds_write_b128 v171, v[10:13] offset:26624
	v_or_b32_e32 v2, s3, v33
	v_cvt_f32_i32_e32 v172, v2
	v_and_or_b32 v2, v26, 3, v173
	v_lshlrev_b32_e32 v3, 1, v32
	v_mad_u32_u24 v22, v33, s6, 0
	v_lshl_add_u32 v2, v2, 6, 0
	v_and_b32_e32 v3, 32, v3
	s_or_b32 s6, s49, s9
	v_exp_f32_e32 v27, v28
	v_add3_u32 v174, v2, v3, v25
	v_mov_b32_e32 v2, s6
	v_mov_b32_e32 v3, s48
	v_mad_u64_u32 v[2:3], s[6:7], v24, s7, v[2:3]
	v_and_b32_e32 v4, 3, v32
	v_lshl_or_b32 v2, v4, 4, v2
	v_lshl_add_u64 v[4:5], v[2:3], 0, v[20:21]
	v_lshl_add_u64 v[2:3], v[2:3], 0, v[18:19]
	v_mov_b32_e32 v16, v151
	v_mov_b32_e32 v17, v151
	v_mbcnt_lo_u32_b32 v18, -1, 0
	v_mul_f32_e32 v142, 0x3fb8aa3b, v27
	v_lshl_add_u64 v[146:147], s[16:17], 0, v[4:5]
	v_lshl_add_u64 v[148:149], s[16:17], 0, v[2:3]
	v_mov_b32_e32 v2, v151
	v_mov_b32_e32 v3, v151
	v_mov_b32_e32 v4, v151
	v_mov_b32_e32 v5, v151
	v_mov_b32_e32 v6, v151
	v_mov_b32_e32 v7, v151
	v_mov_b32_e32 v8, v151
	v_mov_b32_e32 v9, v151
	v_mov_b32_e32 v10, v151
	v_mov_b32_e32 v11, v151
	v_mov_b32_e32 v12, v151
	v_mov_b32_e32 v13, v151
	v_mov_b32_e32 v14, v151
	v_mov_b32_e32 v15, v151
	s_mov_b32 s10, -2.0
	v_add_u32_e32 v175, v22, v150
	v_mbcnt_hi_u32_b32 v170, -1, v18
	v_mov_b64_e32 v[32:33], v[16:17]
	v_mov_b64_e32 v[48:49], v[16:17]
	v_mov_b64_e32 v[64:65], v[16:17]
	v_mov_b32_e32 v143, v142
	s_mov_b64 s[6:7], 0
	s_mov_b32 s8, 0xc2000000
	s_mov_b32 s11, 0xc0400000
	v_mov_b64_e32 v[30:31], v[14:15]
	v_mov_b64_e32 v[28:29], v[12:13]
	v_mov_b64_e32 v[26:27], v[10:11]
	v_mov_b64_e32 v[24:25], v[8:9]
	v_mov_b64_e32 v[22:23], v[6:7]
	v_mov_b64_e32 v[20:21], v[4:5]
	v_mov_b64_e32 v[18:19], v[2:3]
	v_mov_b64_e32 v[46:47], v[14:15]
	v_mov_b64_e32 v[44:45], v[12:13]
	v_mov_b64_e32 v[42:43], v[10:11]
	v_mov_b64_e32 v[40:41], v[8:9]
	v_mov_b64_e32 v[38:39], v[6:7]
	v_mov_b64_e32 v[36:37], v[4:5]
	v_mov_b64_e32 v[34:35], v[2:3]
	v_mov_b64_e32 v[62:63], v[14:15]
	v_mov_b64_e32 v[60:61], v[12:13]
	v_mov_b64_e32 v[58:59], v[10:11]
	v_mov_b64_e32 v[56:57], v[8:9]
	v_mov_b64_e32 v[54:55], v[6:7]
	v_mov_b64_e32 v[52:53], v[4:5]
	v_mov_b64_e32 v[50:51], v[2:3]
	v_mbcnt_lo_u32_b32 v239, -1, 0
	v_mbcnt_hi_u32_b32 v239, -1, v239
	v_and_b32_e32 v238, 31, v239
	v_lshrrev_b32_e32 v237, 3, v238
	v_and_b32_e32 v236, 3, v238
	v_lshl_add_u32 v237, v237, 2, v236
	v_bfe_u32 v236, v238, 2, 1
	v_lshlrev_b32_e32 v236, 2, v236
	v_mov_b32_e32 v233, 0
	v_mov_b32_e32 v234, 0
	v_cmp_eq_u32_e64 s[98:99], 0, v237
	v_cndmask_b32_e64 v233, v233, 32, s[98:99]
	v_cndmask_b32_e64 v234, v234, 34, s[98:99]
	v_cmp_eq_u32_e64 s[98:99], 1, v237
	v_cndmask_b32_e64 v233, v233, 33, s[98:99]
	v_cndmask_b32_e64 v234, v234, 35, s[98:99]
	v_cmp_eq_u32_e64 s[98:99], 2, v237
	v_cndmask_b32_e64 v233, v233, 48, s[98:99]
	v_cndmask_b32_e64 v234, v234, 42, s[98:99]
	v_cmp_eq_u32_e64 s[98:99], 3, v237
	v_cndmask_b32_e64 v233, v233, 49, s[98:99]
	v_cndmask_b32_e64 v234, v234, 43, s[98:99]
	v_cmp_eq_u32_e64 s[98:99], 4, v237
	v_cndmask_b32_e64 v233, v233, 40, s[98:99]
	v_cndmask_b32_e64 v234, v234, 0, s[98:99]
	v_cmp_eq_u32_e64 s[98:99], 5, v237
	v_cndmask_b32_e64 v233, v233, 41, s[98:99]
	v_cndmask_b32_e64 v234, v234, 1, s[98:99]
	v_cmp_eq_u32_e64 s[98:99], 6, v237
	v_cndmask_b32_e64 v233, v233, 50, s[98:99]
	v_cndmask_b32_e64 v234, v234, 16, s[98:99]
	v_cmp_eq_u32_e64 s[98:99], 7, v237
	v_cndmask_b32_e64 v233, v233, 51, s[98:99]
	v_cndmask_b32_e64 v234, v234, 17, s[98:99]
	v_cmp_eq_u32_e64 s[98:99], 8, v237
	v_cndmask_b32_e64 v233, v233, 56, s[98:99]
	v_cndmask_b32_e64 v234, v234, 2, s[98:99]
	v_cmp_eq_u32_e64 s[98:99], 9, v237
	v_cndmask_b32_e64 v233, v233, 57, s[98:99]
	v_cndmask_b32_e64 v234, v234, 3, s[98:99]
	v_cmp_eq_u32_e64 s[98:99], 10, v237
	v_cndmask_b32_e64 v233, v233, 58, s[98:99]
	v_cndmask_b32_e64 v234, v234, 18, s[98:99]
	v_cmp_eq_u32_e64 s[98:99], 11, v237
	v_cndmask_b32_e64 v233, v233, 59, s[98:99]
	v_cndmask_b32_e64 v234, v234, 19, s[98:99]
	v_cmp_eq_u32_e64 s[98:99], 12, v237
	v_cndmask_b32_e64 v233, v233, 24, s[98:99]
	v_cndmask_b32_e64 v234, v234, 8, s[98:99]
	v_cmp_eq_u32_e64 s[98:99], 13, v237
	v_cndmask_b32_e64 v233, v233, 25, s[98:99]
	v_cndmask_b32_e64 v234, v234, 9, s[98:99]
	v_cmp_eq_u32_e64 s[98:99], 14, v237
	v_cndmask_b32_e64 v233, v233, 26, s[98:99]
	v_cndmask_b32_e64 v234, v234, 10, s[98:99]
	v_cmp_eq_u32_e64 s[98:99], 15, v237
	v_cndmask_b32_e64 v233, v233, 27, s[98:99]
	v_cndmask_b32_e64 v234, v234, 11, s[98:99]
	v_add_u32_e32 v233, v233, v236
	v_add_u32_e32 v234, v234, v236
	v_mul_u32_u24_e32 v235, 0x90, v238
	v_mul_u32_u24_e32 v240, 0x90, v233
	v_mul_u32_u24_e32 v241, 0x90, v234
	v_sub_u32_e32 v240, v240, v235
	v_sub_u32_e32 v241, v241, v235
	v_add_u32_e32 v240, v240, v175
	v_add_u32_e32 v241, v241, v175
	v_cvt_f32_u32_e32 v233, v233
	v_cvt_f32_u32_e32 v234, v234
	v_mul_f32_e32 v233, v142, v233
	v_mul_f32_e32 v234, v142, v234
	v_cmp_gt_u32_e64 s[98:99], 32, v239
	v_cndmask_b32_e64 v242, v233, 1.0, s[98:99]
	v_cndmask_b32_e64 v243, v234, 1.0, s[98:99]
	v_xor_b32_e32 v233, 0x80000000, v233
	v_xor_b32_e32 v234, 0x80000000, v234
	v_cndmask_b32_e64 v244, v233, 1.0, s[98:99]
	v_cndmask_b32_e64 v245, v234, 1.0, s[98:99]
	v_xor_b32_e32 v231, 0x80000000, v142
	v_cndmask_b32_e64 v231, 0, v231, s[98:99]
	v_cndmask_b32_e64 v232, 1.0, 0, s[98:99]
	s_branch .LBB0_2004

; #define LAS __attribute__((address_space(3)))
; #define PHASE(n) if (ph_lo <= (n) && (n) < ph_hi) { phase_body<n>(lds, vcu, NGW); if ((n) + 1 < ph_hi) { if (ph_hi > NPHASE) { __syncthreads(); cg::this_grid().sync(); } else xcd_barrier(xbar); } }
; __global__ void __launch_bounds__(512, 2) fwd_mega(Params Pv) {
;     extern __shared__ __attribute__((aligned(16))) unsigned char lds_raw[];
;     LAS unsigned char* lds = (LAS unsigned char*)lds_raw;
;     const int G = gridDim.x, bx = blockIdx.x; const int vcu = (G % 8 == 0) ? (bx % 8) * (G / 8) + bx / 8 : bx; const int NGW = G * 8;
;     const int ph_lo = Pv.ph_lo, ph_hi = Pv.ph_hi;
;     volatile LAS unsigned* bst = (volatile LAS unsigned*)(lds + 147456);
;     if (threadIdx.x < 2) bst[threadIdx.x] = 0u;
;     __syncthreads();
;     XcdBarrier xbar = xcd_barrier_post((unsigned*)(Pv.ws + OFF_CTL), bst);
;     ...
;     PHASE(0) PHASE(1) PHASE(2) PHASE(3) PHASE(4) PHASE(5) PHASE(6) PHASE(7) PHASE(8) PHASE(9) PHASE(10)
;     PHASE(11) PHASE(12) PHASE(13) PHASE(14) PHASE(15) PHASE(16) PHASE(17) PHASE(18) PHASE(19) PHASE(20)
;     ...
; }
	.amdhsa_kernel _Z8fwd_mega6Params
		.amdhsa_group_segment_fixed_size 0
		.amdhsa_private_segment_fixed_size 0
		.amdhsa_kernarg_size 552
		.amdhsa_user_sgpr_count 2
		.amdhsa_user_sgpr_dispatch_ptr 0
		.amdhsa_user_sgpr_queue_ptr 0
		.amdhsa_user_sgpr_kernarg_segment_ptr 1
		.amdhsa_user_sgpr_dispatch_id 0
		.amdhsa_user_sgpr_kernarg_preload_length 0
		.amdhsa_user_sgpr_kernarg_preload_offset 0
		.amdhsa_user_sgpr_private_segment_size 0
		.amdhsa_uses_dynamic_stack 0
		.amdhsa_enable_private_segment 0
		.amdhsa_system_sgpr_workgroup_id_x 1
		.amdhsa_system_sgpr_workgroup_id_y 0
		.amdhsa_system_sgpr_workgroup_id_z 0
		.amdhsa_system_sgpr_workgroup_info 0
		.amdhsa_system_vgpr_workitem_id 2
		.amdhsa_next_free_vgpr 256
		.amdhsa_next_free_sgpr 102
		.amdhsa_accum_offset 256
		.amdhsa_reserve_vcc 1
		.amdhsa_float_round_mode_32 0
		.amdhsa_float_round_mode_16_64 0
		.amdhsa_float_denorm_mode_32 3
		.amdhsa_float_denorm_mode_16_64 3
		.amdhsa_dx10_clamp 1
		.amdhsa_ieee_mode 1
		.amdhsa_fp16_overflow 0
		.amdhsa_tg_split 0
		.amdhsa_exception_fp_ieee_invalid_op 0
		.amdhsa_exception_fp_denorm_src 0
		.amdhsa_exception_fp_ieee_div_zero 0
		.amdhsa_exception_fp_ieee_overflow 0
		.amdhsa_exception_fp_ieee_underflow 0
		.amdhsa_exception_fp_ieee_inexact 0
		.amdhsa_exception_int_div_zero 0
	.end_amdhsa_kernel

; #define LAS __attribute__((address_space(3)))
; #define PHASE(n) if (ph_lo <= (n) && (n) < ph_hi) { phase_body<n>(lds, vcu, NGW); if ((n) + 1 < ph_hi) { if (ph_hi > NPHASE) { __syncthreads(); cg::this_grid().sync(); } else xcd_barrier(xbar); } }
; __global__ void __launch_bounds__(512, 2) fwd_mega(Params Pv) {
;     extern __shared__ __attribute__((aligned(16))) unsigned char lds_raw[];
;     LAS unsigned char* lds = (LAS unsigned char*)lds_raw;
;     const int G = gridDim.x, bx = blockIdx.x; const int vcu = (G % 8 == 0) ? (bx % 8) * (G / 8) + bx / 8 : bx; const int NGW = G * 8;
;     const int ph_lo = Pv.ph_lo, ph_hi = Pv.ph_hi;
;     volatile LAS unsigned* bst = (volatile LAS unsigned*)(lds + 147456);
;     if (threadIdx.x < 2) bst[threadIdx.x] = 0u;
;     __syncthreads();
;     XcdBarrier xbar = xcd_barrier_post((unsigned*)(Pv.ws + OFF_CTL), bst);
;     ...
;     PHASE(0) PHASE(1) PHASE(2) PHASE(3) PHASE(4) PHASE(5) PHASE(6) PHASE(7) PHASE(8) PHASE(9) PHASE(10)
;     PHASE(11) PHASE(12) PHASE(13) PHASE(14) PHASE(15) PHASE(16) PHASE(17) PHASE(18) PHASE(19) PHASE(20)
;     ...
; }
amdhsa.kernels:
  - .agpr_count:     0
    .args:
      - .offset:         0
        .size:           296
        .value_kind:     by_value
      - .offset:         296
        .size:           4
        .value_kind:     hidden_block_count_x
      - .offset:         300
        .size:           4
        .value_kind:     hidden_block_count_y
      - .offset:         304
        .size:           4
        .value_kind:     hidden_block_count_z
      - .offset:         308
        .size:           2
        .value_kind:     hidden_group_size_x
      - .offset:         310
        .size:           2
        .value_kind:     hidden_group_size_y
      - .offset:         312
        .size:           2
        .value_kind:     hidden_group_size_z
      - .offset:         314
        .size:           2
        .value_kind:     hidden_remainder_x
      - .offset:         316
        .size:           2
        .value_kind:     hidden_remainder_y
      - .offset:         318
        .size:           2
        .value_kind:     hidden_remainder_z
      - .offset:         336
        .size:           8
        .value_kind:     hidden_global_offset_x
      - .offset:         344
        .size:           8
        .value_kind:     hidden_global_offset_y
      - .offset:         352
        .size:           8
        .value_kind:     hidden_global_offset_z
      - .offset:         360
        .size:           2
        .value_kind:     hidden_grid_dims
      - .offset:         384
        .size:           8
        .value_kind:     hidden_multigrid_sync_arg
      - .offset:         416
        .size:           4
        .value_kind:     hidden_dynamic_lds_size
    .group_segment_fixed_size: 0
    .kernarg_segment_align: 8
    .kernarg_segment_size: 552
    .language:       OpenCL C
    .language_version:
      - 2
      - 0
    .max_flat_workgroup_size: 512
    .name:           _Z8fwd_mega6Params
    .private_segment_fixed_size: 0
    .sgpr_count:     108
    .sgpr_spill_count: 0
    .symbol:         _Z8fwd_mega6Params.kd
    .uniform_work_group_size: 1
    .uses_dynamic_stack: false
    .vgpr_count:     256
    .vgpr_spill_count: 0
    .wavefront_size: 64
